# th5 plus last K-loop iteration of each unit peeled without the closing barrier (branch-free form of the exit-barrier skip)
# baseline (speedup 1.0000x reference)
.LBB0_255:
	s_ashr_i32 s17, s16, 31
	s_lshl_b64 s[8:9], s[16:17], 20
	v_readlane_b32 s18, v254, 39
	v_readlane_b32 s19, v254, 40
	s_add_u32 s18, s18, s8
	s_addc_u32 s19, s19, s9
	s_and_b64 s[8:9], s[36:37], exec
	s_cselect_b32 s8, s19, s3
	s_cselect_b32 s9, s18, s2
	s_ashr_i32 s15, s14, 31
	s_lshl_b64 s[20:21], s[14:15], 20
	s_add_u32 s20, s29, s20
	s_addc_u32 s21, s38, s21
	s_and_b64 s[26:27], s[36:37], exec
	s_cselect_b32 s15, s21, s23
	s_cselect_b32 s17, s20, s22
	s_add_u32 s2, s2, 0x80800
	s_addc_u32 s3, s3, 0
	s_add_u32 s33, s22, 0x100
	s_addc_u32 s34, s23, 0
	s_mov_b32 s35, -2
	s_add_u32 s22, s2, 0xfff80800
	s_addc_u32 s23, s3, -1
	s_add_i32 s48, 0, 0x10000
	s_cmp_eq_u32 s35, 28
	s_cselect_b32 s27, s8, s23
	s_cselect_b32 s26, s9, s22
	s_cselect_b32 s23, s15, s34
	s_cselect_b32 s22, s17, s33
	s_add_i32 s50, 0, 0x14000
	v_add_u32_e32 v176, s48, v191
	v_add_u32_e32 v188, s50, v191
	ds_read_b128 v[148:151], v176
	ds_read_b128 v[152:155], v176 offset:1024
	ds_read_b128 v[172:175], v176 offset:2048
	ds_read_b128 v[176:179], v176 offset:3072
	ds_read_b128 v[180:183], v188
	ds_read_b128 v[184:187], v188 offset:1024
	ds_read_b128 v[196:199], v188 offset:2048
	ds_read_b128 v[200:203], v188 offset:3072
	s_add_i32 m0, s39, 0xc000
	ds_read_b128 v[204:207], v194
	ds_read_b128 v[212:215], v194 offset:1024
	ds_read_b128 v[216:219], v194 offset:2048
	ds_read_b128 v[220:223], v194 offset:3072
	ds_read_b128 v[224:227], v194 offset:4096
	ds_read_b128 v[228:231], v194 offset:5120
	ds_read_b128 v[232:235], v194 offset:6144
	ds_read_b128 v[236:239], v194 offset:7168
	global_load_lds_dwordx4 v168, s[2:3]
	s_add_i32 m0, s39, 0xe000
	s_nop 0
	global_load_lds_dwordx4 v170, s[2:3]
	s_waitcnt vmcnt(8)
	s_waitcnt lgkmcnt(0)
	s_setprio 1
	s_barrier
	v_mfma_f32_16x16x32_bf16 v[144:147], v[148:151], v[204:207], 0
	v_mfma_f32_16x16x32_bf16 v[136:139], v[172:175], v[204:207], 0
	v_mfma_f32_16x16x32_bf16 v[128:131], v[148:151], v[216:219], 0
	v_mfma_f32_16x16x32_bf16 v[120:123], v[172:175], v[216:219], 0
	v_mfma_f32_16x16x32_bf16 v[112:115], v[148:151], v[224:227], 0
	v_mfma_f32_16x16x32_bf16 v[104:107], v[172:175], v[224:227], 0
	v_mfma_f32_16x16x32_bf16 v[96:99], v[148:151], v[232:235], 0
	v_mfma_f32_16x16x32_bf16 v[88:91], v[172:175], v[232:235], 0
	v_mfma_f32_16x16x32_bf16 v[144:147], v[152:155], v[212:215], v[144:147]
	v_mfma_f32_16x16x32_bf16 v[136:139], v[176:179], v[212:215], v[136:139]
	v_mfma_f32_16x16x32_bf16 v[128:131], v[152:155], v[220:223], v[128:131]
	v_mfma_f32_16x16x32_bf16 v[120:123], v[176:179], v[220:223], v[120:123]
	v_mfma_f32_16x16x32_bf16 v[112:115], v[152:155], v[228:231], v[112:115]
	v_mfma_f32_16x16x32_bf16 v[104:107], v[176:179], v[228:231], v[104:107]
	v_mfma_f32_16x16x32_bf16 v[96:99], v[152:155], v[236:239], v[96:99]
	v_mfma_f32_16x16x32_bf16 v[88:91], v[176:179], v[236:239], v[88:91]
	v_mfma_f32_16x16x32_bf16 v[140:143], v[180:183], v[204:207], 0
	v_mfma_f32_16x16x32_bf16 v[132:135], v[196:199], v[204:207], 0
	v_mfma_f32_16x16x32_bf16 v[124:127], v[180:183], v[216:219], 0
	v_mfma_f32_16x16x32_bf16 v[116:119], v[196:199], v[216:219], 0
	v_mfma_f32_16x16x32_bf16 v[108:111], v[180:183], v[224:227], 0
	v_mfma_f32_16x16x32_bf16 v[100:103], v[196:199], v[224:227], 0
	v_mfma_f32_16x16x32_bf16 v[92:95], v[180:183], v[232:235], 0
	v_mfma_f32_16x16x32_bf16 v[84:87], v[196:199], v[232:235], 0
	v_mfma_f32_16x16x32_bf16 v[140:143], v[184:187], v[212:215], v[140:143]
	v_mfma_f32_16x16x32_bf16 v[132:135], v[200:203], v[212:215], v[132:135]
	v_mfma_f32_16x16x32_bf16 v[124:127], v[184:187], v[220:223], v[124:127]
	v_mfma_f32_16x16x32_bf16 v[116:119], v[200:203], v[220:223], v[116:119]
	v_mfma_f32_16x16x32_bf16 v[108:111], v[184:187], v[228:231], v[108:111]
	v_mfma_f32_16x16x32_bf16 v[100:103], v[200:203], v[228:231], v[100:103]
	v_mfma_f32_16x16x32_bf16 v[92:95], v[184:187], v[236:239], v[92:95]
	v_mfma_f32_16x16x32_bf16 v[84:87], v[200:203], v[236:239], v[84:87]
	s_barrier
	s_setprio 0
	s_add_i32 s48, s48, s28
	s_add_u32 s98, s22, 0x80
	s_addc_u32 s99, s23, 0
	s_add_u32 s100, s26, 0x800
	s_addc_u32 s101, s27, 0
	s_mov_b32 m0, s48
	ds_read_b128 v[204:207], v194 offset:16384
	ds_read_b128 v[212:215], v194 offset:17408
	ds_read_b128 v[216:219], v194 offset:18432
	ds_read_b128 v[220:223], v194 offset:19456
	ds_read_b128 v[224:227], v194 offset:20480
	ds_read_b128 v[228:231], v194 offset:21504
	ds_read_b128 v[232:235], v194 offset:22528
	ds_read_b128 v[236:239], v194 offset:23552
	global_load_lds_dwordx4 v2, s[22:23]
	s_add_i32 m0, s48, 0x2000
	s_add_u32 s48, s22, 0x80000
	s_addc_u32 s49, s23, 0
	s_add_i32 s50, s50, s28
	global_load_lds_dwordx4 v156, s[22:23]
	s_mov_b32 m0, s50
	s_nop 0
	global_load_lds_dwordx4 v2, s[48:49]
	s_add_i32 m0, s50, 0x2000
	s_nop 0
	global_load_lds_dwordx4 v156, s[48:49]
	s_mov_b32 m0, s39
	s_nop 0
	global_load_lds_dwordx4 v160, s[26:27]
	s_mov_b32 m0, s41
	s_nop 0
	global_load_lds_dwordx4 v158, s[26:27]
	s_waitcnt vmcnt(8)
	s_waitcnt lgkmcnt(0)
	s_setprio 1
	s_barrier
	v_mfma_f32_16x16x32_bf16 v[80:83], v[148:151], v[204:207], 0
	v_mfma_f32_16x16x32_bf16 v[72:75], v[172:175], v[204:207], 0
	v_mfma_f32_16x16x32_bf16 v[64:67], v[148:151], v[216:219], 0
	v_mfma_f32_16x16x32_bf16 v[56:59], v[172:175], v[216:219], 0
	v_mfma_f32_16x16x32_bf16 v[48:51], v[148:151], v[224:227], 0
	v_mfma_f32_16x16x32_bf16 v[40:43], v[172:175], v[224:227], 0
	v_mfma_f32_16x16x32_bf16 v[32:35], v[148:151], v[232:235], 0
	v_mfma_f32_16x16x32_bf16 v[24:27], v[172:175], v[232:235], 0
	v_mfma_f32_16x16x32_bf16 v[80:83], v[152:155], v[212:215], v[80:83]
	v_mfma_f32_16x16x32_bf16 v[72:75], v[176:179], v[212:215], v[72:75]
	v_mfma_f32_16x16x32_bf16 v[64:67], v[152:155], v[220:223], v[64:67]
	v_mfma_f32_16x16x32_bf16 v[56:59], v[176:179], v[220:223], v[56:59]
	v_mfma_f32_16x16x32_bf16 v[48:51], v[152:155], v[228:231], v[48:51]
	v_mfma_f32_16x16x32_bf16 v[40:43], v[176:179], v[228:231], v[40:43]
	v_mfma_f32_16x16x32_bf16 v[32:35], v[152:155], v[236:239], v[32:35]
	v_mfma_f32_16x16x32_bf16 v[24:27], v[176:179], v[236:239], v[24:27]
	v_mfma_f32_16x16x32_bf16 v[76:79], v[180:183], v[204:207], 0
	v_mfma_f32_16x16x32_bf16 v[68:71], v[196:199], v[204:207], 0
	v_mfma_f32_16x16x32_bf16 v[60:63], v[180:183], v[216:219], 0
	v_mfma_f32_16x16x32_bf16 v[52:55], v[196:199], v[216:219], 0
	v_mfma_f32_16x16x32_bf16 v[44:47], v[180:183], v[224:227], 0
	v_mfma_f32_16x16x32_bf16 v[36:39], v[196:199], v[224:227], 0
	v_mfma_f32_16x16x32_bf16 v[28:31], v[180:183], v[232:235], 0
	v_mfma_f32_16x16x32_bf16 v[20:23], v[196:199], v[232:235], 0
	v_mfma_f32_16x16x32_bf16 v[76:79], v[184:187], v[212:215], v[76:79]
	v_mfma_f32_16x16x32_bf16 v[68:71], v[200:203], v[212:215], v[68:71]
	v_mfma_f32_16x16x32_bf16 v[60:63], v[184:187], v[220:223], v[60:63]
	v_mfma_f32_16x16x32_bf16 v[52:55], v[200:203], v[220:223], v[52:55]
	v_mfma_f32_16x16x32_bf16 v[44:47], v[184:187], v[228:231], v[44:47]
	v_mfma_f32_16x16x32_bf16 v[36:39], v[200:203], v[228:231], v[36:39]
	v_mfma_f32_16x16x32_bf16 v[28:31], v[184:187], v[236:239], v[28:31]
	v_mfma_f32_16x16x32_bf16 v[20:23], v[200:203], v[236:239], v[20:23]
	s_barrier
	s_setprio 0
	s_add_i32 s48, 0, 0x18000
	s_add_i32 s49, 0, 0x1c000
	v_add_u32_e32 v176, s48, v191
	v_add_u32_e32 v195, s49, v191
	ds_read_b128 v[148:151], v176
	ds_read_b128 v[152:155], v176 offset:1024
	ds_read_b128 v[172:175], v176 offset:2048
	ds_read_b128 v[176:179], v176 offset:3072
	ds_read_b128 v[180:183], v195
	ds_read_b128 v[184:187], v195 offset:1024
	ds_read_b128 v[196:199], v195 offset:2048
	ds_read_b128 v[200:203], v195 offset:3072
	s_add_u32 s26, s26, 0x80000
	s_addc_u32 s27, s27, 0
	s_mov_b32 m0, s42
	ds_read_b128 v[204:207], v194 offset:32768
	ds_read_b128 v[212:215], v194 offset:33792
	ds_read_b128 v[216:219], v194 offset:34816
	ds_read_b128 v[220:223], v194 offset:35840
	ds_read_b128 v[224:227], v194 offset:36864
	ds_read_b128 v[228:231], v194 offset:37888
	ds_read_b128 v[232:235], v194 offset:38912
	ds_read_b128 v[236:239], v194 offset:39936
	global_load_lds_dwordx4 v160, s[26:27]
	s_mov_b32 m0, s43
	s_nop 0
	global_load_lds_dwordx4 v158, s[26:27]
	s_waitcnt vmcnt(8)
	s_waitcnt lgkmcnt(0)
	s_setprio 1
	s_barrier
	v_mfma_f32_16x16x32_bf16 v[144:147], v[148:151], v[204:207], v[144:147]
	v_mfma_f32_16x16x32_bf16 v[136:139], v[172:175], v[204:207], v[136:139]
	v_mfma_f32_16x16x32_bf16 v[128:131], v[148:151], v[216:219], v[128:131]
	v_mfma_f32_16x16x32_bf16 v[120:123], v[172:175], v[216:219], v[120:123]
	v_mfma_f32_16x16x32_bf16 v[112:115], v[148:151], v[224:227], v[112:115]
	v_mfma_f32_16x16x32_bf16 v[104:107], v[172:175], v[224:227], v[104:107]
	v_mfma_f32_16x16x32_bf16 v[96:99], v[148:151], v[232:235], v[96:99]
	v_mfma_f32_16x16x32_bf16 v[88:91], v[172:175], v[232:235], v[88:91]
	v_mfma_f32_16x16x32_bf16 v[144:147], v[152:155], v[212:215], v[144:147]
	v_mfma_f32_16x16x32_bf16 v[136:139], v[176:179], v[212:215], v[136:139]
	v_mfma_f32_16x16x32_bf16 v[128:131], v[152:155], v[220:223], v[128:131]
	v_mfma_f32_16x16x32_bf16 v[120:123], v[176:179], v[220:223], v[120:123]
	v_mfma_f32_16x16x32_bf16 v[112:115], v[152:155], v[228:231], v[112:115]
	v_mfma_f32_16x16x32_bf16 v[104:107], v[176:179], v[228:231], v[104:107]
	v_mfma_f32_16x16x32_bf16 v[96:99], v[152:155], v[236:239], v[96:99]
	v_mfma_f32_16x16x32_bf16 v[88:91], v[176:179], v[236:239], v[88:91]
	v_mfma_f32_16x16x32_bf16 v[140:143], v[180:183], v[204:207], v[140:143]
	v_mfma_f32_16x16x32_bf16 v[132:135], v[196:199], v[204:207], v[132:135]
	v_mfma_f32_16x16x32_bf16 v[124:127], v[180:183], v[216:219], v[124:127]
	v_mfma_f32_16x16x32_bf16 v[116:119], v[196:199], v[216:219], v[116:119]
	v_mfma_f32_16x16x32_bf16 v[108:111], v[180:183], v[224:227], v[108:111]
	v_mfma_f32_16x16x32_bf16 v[100:103], v[196:199], v[224:227], v[100:103]
	v_mfma_f32_16x16x32_bf16 v[92:95], v[180:183], v[232:235], v[92:95]
	v_mfma_f32_16x16x32_bf16 v[84:87], v[196:199], v[232:235], v[84:87]
	v_mfma_f32_16x16x32_bf16 v[140:143], v[184:187], v[212:215], v[140:143]
	v_mfma_f32_16x16x32_bf16 v[132:135], v[200:203], v[212:215], v[132:135]
	v_mfma_f32_16x16x32_bf16 v[124:127], v[184:187], v[220:223], v[124:127]
	v_mfma_f32_16x16x32_bf16 v[116:119], v[200:203], v[220:223], v[116:119]
	v_mfma_f32_16x16x32_bf16 v[108:111], v[184:187], v[228:231], v[108:111]
	v_mfma_f32_16x16x32_bf16 v[100:103], v[200:203], v[228:231], v[100:103]
	v_mfma_f32_16x16x32_bf16 v[92:95], v[184:187], v[236:239], v[92:95]
	v_mfma_f32_16x16x32_bf16 v[84:87], v[200:203], v[236:239], v[84:87]
	s_barrier
	s_setprio 0
	s_add_i32 s26, s48, s28
	s_mov_b32 m0, s26
	ds_read_b128 v[204:207], v194 offset:49152
	ds_read_b128 v[212:215], v194 offset:50176
	ds_read_b128 v[216:219], v194 offset:51200
	ds_read_b128 v[220:223], v194 offset:52224
	ds_read_b128 v[224:227], v194 offset:53248
	ds_read_b128 v[228:231], v194 offset:54272
	ds_read_b128 v[232:235], v194 offset:55296
	ds_read_b128 v[236:239], v194 offset:56320
	global_load_lds_dwordx4 v2, s[98:99]
	s_add_i32 m0, s26, 0x2000
	s_add_u32 s22, s22, 0x80080
	s_addc_u32 s23, s23, 0
	s_add_i32 s26, s49, s28
	global_load_lds_dwordx4 v156, s[98:99]
	s_mov_b32 m0, s26
	s_nop 0
	global_load_lds_dwordx4 v2, s[22:23]
	s_add_i32 m0, s26, 0x2000
	s_nop 0
	global_load_lds_dwordx4 v156, s[22:23]
	s_mov_b32 m0, s44
	s_nop 0
	global_load_lds_dwordx4 v160, s[100:101]
	s_mov_b32 m0, s45
	s_nop 0
	global_load_lds_dwordx4 v158, s[100:101]
	s_waitcnt vmcnt(8)
	s_waitcnt lgkmcnt(0)
	s_setprio 1
	s_barrier
	v_mfma_f32_16x16x32_bf16 v[80:83], v[148:151], v[204:207], v[80:83]
	v_mfma_f32_16x16x32_bf16 v[72:75], v[172:175], v[204:207], v[72:75]
	v_mfma_f32_16x16x32_bf16 v[64:67], v[148:151], v[216:219], v[64:67]
	v_mfma_f32_16x16x32_bf16 v[56:59], v[172:175], v[216:219], v[56:59]
	v_mfma_f32_16x16x32_bf16 v[48:51], v[148:151], v[224:227], v[48:51]
	v_mfma_f32_16x16x32_bf16 v[40:43], v[172:175], v[224:227], v[40:43]
	v_mfma_f32_16x16x32_bf16 v[32:35], v[148:151], v[232:235], v[32:35]
	v_mfma_f32_16x16x32_bf16 v[24:27], v[172:175], v[232:235], v[24:27]
	v_mfma_f32_16x16x32_bf16 v[80:83], v[152:155], v[212:215], v[80:83]
	v_mfma_f32_16x16x32_bf16 v[72:75], v[176:179], v[212:215], v[72:75]
	v_mfma_f32_16x16x32_bf16 v[64:67], v[152:155], v[220:223], v[64:67]
	v_mfma_f32_16x16x32_bf16 v[56:59], v[176:179], v[220:223], v[56:59]
	v_mfma_f32_16x16x32_bf16 v[48:51], v[152:155], v[228:231], v[48:51]
	v_mfma_f32_16x16x32_bf16 v[40:43], v[176:179], v[228:231], v[40:43]
	v_mfma_f32_16x16x32_bf16 v[32:35], v[152:155], v[236:239], v[32:35]
	v_mfma_f32_16x16x32_bf16 v[24:27], v[176:179], v[236:239], v[24:27]
	v_mfma_f32_16x16x32_bf16 v[76:79], v[180:183], v[204:207], v[76:79]
	v_mfma_f32_16x16x32_bf16 v[68:71], v[196:199], v[204:207], v[68:71]
	v_mfma_f32_16x16x32_bf16 v[60:63], v[180:183], v[216:219], v[60:63]
	v_mfma_f32_16x16x32_bf16 v[52:55], v[196:199], v[216:219], v[52:55]
	v_mfma_f32_16x16x32_bf16 v[44:47], v[180:183], v[224:227], v[44:47]
	v_mfma_f32_16x16x32_bf16 v[36:39], v[196:199], v[224:227], v[36:39]
	v_mfma_f32_16x16x32_bf16 v[28:31], v[180:183], v[232:235], v[28:31]
	v_mfma_f32_16x16x32_bf16 v[20:23], v[196:199], v[232:235], v[20:23]
	v_mfma_f32_16x16x32_bf16 v[76:79], v[184:187], v[212:215], v[76:79]
	v_mfma_f32_16x16x32_bf16 v[68:71], v[200:203], v[212:215], v[68:71]
	v_mfma_f32_16x16x32_bf16 v[60:63], v[184:187], v[220:223], v[60:63]
	v_mfma_f32_16x16x32_bf16 v[52:55], v[200:203], v[220:223], v[52:55]
	v_mfma_f32_16x16x32_bf16 v[44:47], v[184:187], v[228:231], v[44:47]
	v_mfma_f32_16x16x32_bf16 v[36:39], v[200:203], v[228:231], v[36:39]
	v_mfma_f32_16x16x32_bf16 v[28:31], v[184:187], v[236:239], v[28:31]
	v_mfma_f32_16x16x32_bf16 v[20:23], v[200:203], v[236:239], v[20:23]
	s_barrier
	s_setprio 0
	s_add_i32 s35, s35, 2
	s_add_u32 s2, s2, 0x1000
	s_addc_u32 s3, s3, 0
	s_add_u32 s33, s33, 0x100
	s_addc_u32 s34, s34, 0
	s_cmp_gt_u32 s35, 27
	s_cbranch_scc0 .LBB0_256
	s_branch .Llast_256
.LBB0_256:
	s_add_u32 s22, s2, 0xfff80800
	s_addc_u32 s23, s3, -1
	s_add_i32 s48, 0, 0x10000
	s_cmp_eq_u32 s35, 28
	s_cselect_b32 s27, s8, s23
	s_cselect_b32 s26, s9, s22
	s_cselect_b32 s23, s15, s34
	s_cselect_b32 s22, s17, s33
	s_add_i32 s50, 0, 0x14000
	v_add_u32_e32 v176, s48, v191
	v_add_u32_e32 v188, s50, v191
	ds_read_b128 v[148:151], v176
	ds_read_b128 v[152:155], v176 offset:1024
	ds_read_b128 v[172:175], v176 offset:2048
	ds_read_b128 v[176:179], v176 offset:3072
	ds_read_b128 v[180:183], v188
	ds_read_b128 v[184:187], v188 offset:1024
	ds_read_b128 v[196:199], v188 offset:2048
	ds_read_b128 v[200:203], v188 offset:3072
	s_add_i32 m0, s39, 0xc000
	ds_read_b128 v[204:207], v194
	ds_read_b128 v[212:215], v194 offset:1024
	ds_read_b128 v[216:219], v194 offset:2048
	ds_read_b128 v[220:223], v194 offset:3072
	ds_read_b128 v[224:227], v194 offset:4096
	ds_read_b128 v[228:231], v194 offset:5120
	ds_read_b128 v[232:235], v194 offset:6144
	ds_read_b128 v[236:239], v194 offset:7168
	global_load_lds_dwordx4 v168, s[2:3]
	s_add_i32 m0, s39, 0xe000
	s_nop 0
	global_load_lds_dwordx4 v170, s[2:3]
	s_waitcnt vmcnt(8)
	s_waitcnt lgkmcnt(0)
	s_setprio 1
	s_barrier
	v_mfma_f32_16x16x32_bf16 v[144:147], v[148:151], v[204:207], v[144:147]
	v_mfma_f32_16x16x32_bf16 v[136:139], v[172:175], v[204:207], v[136:139]
	v_mfma_f32_16x16x32_bf16 v[128:131], v[148:151], v[216:219], v[128:131]
	v_mfma_f32_16x16x32_bf16 v[120:123], v[172:175], v[216:219], v[120:123]
	v_mfma_f32_16x16x32_bf16 v[112:115], v[148:151], v[224:227], v[112:115]
	v_mfma_f32_16x16x32_bf16 v[104:107], v[172:175], v[224:227], v[104:107]
	v_mfma_f32_16x16x32_bf16 v[96:99], v[148:151], v[232:235], v[96:99]
	v_mfma_f32_16x16x32_bf16 v[88:91], v[172:175], v[232:235], v[88:91]
	v_mfma_f32_16x16x32_bf16 v[144:147], v[152:155], v[212:215], v[144:147]
	v_mfma_f32_16x16x32_bf16 v[136:139], v[176:179], v[212:215], v[136:139]
	v_mfma_f32_16x16x32_bf16 v[128:131], v[152:155], v[220:223], v[128:131]
	v_mfma_f32_16x16x32_bf16 v[120:123], v[176:179], v[220:223], v[120:123]
	v_mfma_f32_16x16x32_bf16 v[112:115], v[152:155], v[228:231], v[112:115]
	v_mfma_f32_16x16x32_bf16 v[104:107], v[176:179], v[228:231], v[104:107]
	v_mfma_f32_16x16x32_bf16 v[96:99], v[152:155], v[236:239], v[96:99]
	v_mfma_f32_16x16x32_bf16 v[88:91], v[176:179], v[236:239], v[88:91]
	v_mfma_f32_16x16x32_bf16 v[140:143], v[180:183], v[204:207], v[140:143]
	v_mfma_f32_16x16x32_bf16 v[132:135], v[196:199], v[204:207], v[132:135]
	v_mfma_f32_16x16x32_bf16 v[124:127], v[180:183], v[216:219], v[124:127]
	v_mfma_f32_16x16x32_bf16 v[116:119], v[196:199], v[216:219], v[116:119]
	v_mfma_f32_16x16x32_bf16 v[108:111], v[180:183], v[224:227], v[108:111]
	v_mfma_f32_16x16x32_bf16 v[100:103], v[196:199], v[224:227], v[100:103]
	v_mfma_f32_16x16x32_bf16 v[92:95], v[180:183], v[232:235], v[92:95]
	v_mfma_f32_16x16x32_bf16 v[84:87], v[196:199], v[232:235], v[84:87]
	v_mfma_f32_16x16x32_bf16 v[140:143], v[184:187], v[212:215], v[140:143]
	v_mfma_f32_16x16x32_bf16 v[132:135], v[200:203], v[212:215], v[132:135]
	v_mfma_f32_16x16x32_bf16 v[124:127], v[184:187], v[220:223], v[124:127]
	v_mfma_f32_16x16x32_bf16 v[116:119], v[200:203], v[220:223], v[116:119]
	v_mfma_f32_16x16x32_bf16 v[108:111], v[184:187], v[228:231], v[108:111]
	v_mfma_f32_16x16x32_bf16 v[100:103], v[200:203], v[228:231], v[100:103]
	v_mfma_f32_16x16x32_bf16 v[92:95], v[184:187], v[236:239], v[92:95]
	v_mfma_f32_16x16x32_bf16 v[84:87], v[200:203], v[236:239], v[84:87]
	s_barrier
	s_setprio 0
	s_add_i32 s48, s48, s28
	s_add_u32 s98, s22, 0x80
	s_addc_u32 s99, s23, 0
	s_add_u32 s100, s26, 0x800
	s_addc_u32 s101, s27, 0
	s_mov_b32 m0, s48
	ds_read_b128 v[204:207], v194 offset:16384
	ds_read_b128 v[212:215], v194 offset:17408
	ds_read_b128 v[216:219], v194 offset:18432
	ds_read_b128 v[220:223], v194 offset:19456
	ds_read_b128 v[224:227], v194 offset:20480
	ds_read_b128 v[228:231], v194 offset:21504
	ds_read_b128 v[232:235], v194 offset:22528
	ds_read_b128 v[236:239], v194 offset:23552
	global_load_lds_dwordx4 v2, s[22:23]
	s_add_i32 m0, s48, 0x2000
	s_add_u32 s48, s22, 0x80000
	s_addc_u32 s49, s23, 0
	s_add_i32 s50, s50, s28
	global_load_lds_dwordx4 v156, s[22:23]
	s_mov_b32 m0, s50
	s_nop 0
	global_load_lds_dwordx4 v2, s[48:49]
	s_add_i32 m0, s50, 0x2000
	s_nop 0
	global_load_lds_dwordx4 v156, s[48:49]
	s_mov_b32 m0, s39
	s_nop 0
	global_load_lds_dwordx4 v160, s[26:27]
	s_mov_b32 m0, s41
	s_nop 0
	global_load_lds_dwordx4 v158, s[26:27]
	s_waitcnt vmcnt(8)
	s_waitcnt lgkmcnt(0)
	s_setprio 1
	s_barrier
	v_mfma_f32_16x16x32_bf16 v[80:83], v[148:151], v[204:207], v[80:83]
	v_mfma_f32_16x16x32_bf16 v[72:75], v[172:175], v[204:207], v[72:75]
	v_mfma_f32_16x16x32_bf16 v[64:67], v[148:151], v[216:219], v[64:67]
	v_mfma_f32_16x16x32_bf16 v[56:59], v[172:175], v[216:219], v[56:59]
	v_mfma_f32_16x16x32_bf16 v[48:51], v[148:151], v[224:227], v[48:51]
	v_mfma_f32_16x16x32_bf16 v[40:43], v[172:175], v[224:227], v[40:43]
	v_mfma_f32_16x16x32_bf16 v[32:35], v[148:151], v[232:235], v[32:35]
	v_mfma_f32_16x16x32_bf16 v[24:27], v[172:175], v[232:235], v[24:27]
	v_mfma_f32_16x16x32_bf16 v[80:83], v[152:155], v[212:215], v[80:83]
	v_mfma_f32_16x16x32_bf16 v[72:75], v[176:179], v[212:215], v[72:75]
	v_mfma_f32_16x16x32_bf16 v[64:67], v[152:155], v[220:223], v[64:67]
	v_mfma_f32_16x16x32_bf16 v[56:59], v[176:179], v[220:223], v[56:59]
	v_mfma_f32_16x16x32_bf16 v[48:51], v[152:155], v[228:231], v[48:51]
	v_mfma_f32_16x16x32_bf16 v[40:43], v[176:179], v[228:231], v[40:43]
	v_mfma_f32_16x16x32_bf16 v[32:35], v[152:155], v[236:239], v[32:35]
	v_mfma_f32_16x16x32_bf16 v[24:27], v[176:179], v[236:239], v[24:27]
	v_mfma_f32_16x16x32_bf16 v[76:79], v[180:183], v[204:207], v[76:79]
	v_mfma_f32_16x16x32_bf16 v[68:71], v[196:199], v[204:207], v[68:71]
	v_mfma_f32_16x16x32_bf16 v[60:63], v[180:183], v[216:219], v[60:63]
	v_mfma_f32_16x16x32_bf16 v[52:55], v[196:199], v[216:219], v[52:55]
	v_mfma_f32_16x16x32_bf16 v[44:47], v[180:183], v[224:227], v[44:47]
	v_mfma_f32_16x16x32_bf16 v[36:39], v[196:199], v[224:227], v[36:39]
	v_mfma_f32_16x16x32_bf16 v[28:31], v[180:183], v[232:235], v[28:31]
	v_mfma_f32_16x16x32_bf16 v[20:23], v[196:199], v[232:235], v[20:23]
	v_mfma_f32_16x16x32_bf16 v[76:79], v[184:187], v[212:215], v[76:79]
	v_mfma_f32_16x16x32_bf16 v[68:71], v[200:203], v[212:215], v[68:71]
	v_mfma_f32_16x16x32_bf16 v[60:63], v[184:187], v[220:223], v[60:63]
	v_mfma_f32_16x16x32_bf16 v[52:55], v[200:203], v[220:223], v[52:55]
	v_mfma_f32_16x16x32_bf16 v[44:47], v[184:187], v[228:231], v[44:47]
	v_mfma_f32_16x16x32_bf16 v[36:39], v[200:203], v[228:231], v[36:39]
	v_mfma_f32_16x16x32_bf16 v[28:31], v[184:187], v[236:239], v[28:31]
	v_mfma_f32_16x16x32_bf16 v[20:23], v[200:203], v[236:239], v[20:23]
	s_barrier
	s_setprio 0
	s_add_i32 s48, 0, 0x18000
	s_add_i32 s49, 0, 0x1c000
	v_add_u32_e32 v176, s48, v191
	v_add_u32_e32 v195, s49, v191
	ds_read_b128 v[148:151], v176
	ds_read_b128 v[152:155], v176 offset:1024
	ds_read_b128 v[172:175], v176 offset:2048
	ds_read_b128 v[176:179], v176 offset:3072
	ds_read_b128 v[180:183], v195
	ds_read_b128 v[184:187], v195 offset:1024
	ds_read_b128 v[196:199], v195 offset:2048
	ds_read_b128 v[200:203], v195 offset:3072
	s_add_u32 s26, s26, 0x80000
	s_addc_u32 s27, s27, 0
	s_mov_b32 m0, s42
	ds_read_b128 v[204:207], v194 offset:32768
	ds_read_b128 v[212:215], v194 offset:33792
	ds_read_b128 v[216:219], v194 offset:34816
	ds_read_b128 v[220:223], v194 offset:35840
	ds_read_b128 v[224:227], v194 offset:36864
	ds_read_b128 v[228:231], v194 offset:37888
	ds_read_b128 v[232:235], v194 offset:38912
	ds_read_b128 v[236:239], v194 offset:39936
	global_load_lds_dwordx4 v160, s[26:27]
	s_mov_b32 m0, s43
	s_nop 0
	global_load_lds_dwordx4 v158, s[26:27]
	s_waitcnt vmcnt(8)
	s_waitcnt lgkmcnt(0)
	s_setprio 1
	s_barrier
	v_mfma_f32_16x16x32_bf16 v[144:147], v[148:151], v[204:207], v[144:147]
	v_mfma_f32_16x16x32_bf16 v[136:139], v[172:175], v[204:207], v[136:139]
	v_mfma_f32_16x16x32_bf16 v[128:131], v[148:151], v[216:219], v[128:131]
	v_mfma_f32_16x16x32_bf16 v[120:123], v[172:175], v[216:219], v[120:123]
	v_mfma_f32_16x16x32_bf16 v[112:115], v[148:151], v[224:227], v[112:115]
	v_mfma_f32_16x16x32_bf16 v[104:107], v[172:175], v[224:227], v[104:107]
	v_mfma_f32_16x16x32_bf16 v[96:99], v[148:151], v[232:235], v[96:99]
	v_mfma_f32_16x16x32_bf16 v[88:91], v[172:175], v[232:235], v[88:91]
	v_mfma_f32_16x16x32_bf16 v[144:147], v[152:155], v[212:215], v[144:147]
	v_mfma_f32_16x16x32_bf16 v[136:139], v[176:179], v[212:215], v[136:139]
	v_mfma_f32_16x16x32_bf16 v[128:131], v[152:155], v[220:223], v[128:131]
	v_mfma_f32_16x16x32_bf16 v[120:123], v[176:179], v[220:223], v[120:123]
	v_mfma_f32_16x16x32_bf16 v[112:115], v[152:155], v[228:231], v[112:115]
	v_mfma_f32_16x16x32_bf16 v[104:107], v[176:179], v[228:231], v[104:107]
	v_mfma_f32_16x16x32_bf16 v[96:99], v[152:155], v[236:239], v[96:99]
	v_mfma_f32_16x16x32_bf16 v[88:91], v[176:179], v[236:239], v[88:91]
	v_mfma_f32_16x16x32_bf16 v[140:143], v[180:183], v[204:207], v[140:143]
	v_mfma_f32_16x16x32_bf16 v[132:135], v[196:199], v[204:207], v[132:135]
	v_mfma_f32_16x16x32_bf16 v[124:127], v[180:183], v[216:219], v[124:127]
	v_mfma_f32_16x16x32_bf16 v[116:119], v[196:199], v[216:219], v[116:119]
	v_mfma_f32_16x16x32_bf16 v[108:111], v[180:183], v[224:227], v[108:111]
	v_mfma_f32_16x16x32_bf16 v[100:103], v[196:199], v[224:227], v[100:103]
	v_mfma_f32_16x16x32_bf16 v[92:95], v[180:183], v[232:235], v[92:95]
	v_mfma_f32_16x16x32_bf16 v[84:87], v[196:199], v[232:235], v[84:87]
	v_mfma_f32_16x16x32_bf16 v[140:143], v[184:187], v[212:215], v[140:143]
	v_mfma_f32_16x16x32_bf16 v[132:135], v[200:203], v[212:215], v[132:135]
	v_mfma_f32_16x16x32_bf16 v[124:127], v[184:187], v[220:223], v[124:127]
	v_mfma_f32_16x16x32_bf16 v[116:119], v[200:203], v[220:223], v[116:119]
	v_mfma_f32_16x16x32_bf16 v[108:111], v[184:187], v[228:231], v[108:111]
	v_mfma_f32_16x16x32_bf16 v[100:103], v[200:203], v[228:231], v[100:103]
	v_mfma_f32_16x16x32_bf16 v[92:95], v[184:187], v[236:239], v[92:95]
	v_mfma_f32_16x16x32_bf16 v[84:87], v[200:203], v[236:239], v[84:87]
	s_barrier
	s_setprio 0
	s_add_i32 s26, s48, s28
	s_mov_b32 m0, s26
	ds_read_b128 v[204:207], v194 offset:49152
	ds_read_b128 v[212:215], v194 offset:50176
	ds_read_b128 v[216:219], v194 offset:51200
	ds_read_b128 v[220:223], v194 offset:52224
	ds_read_b128 v[224:227], v194 offset:53248
	ds_read_b128 v[228:231], v194 offset:54272
	ds_read_b128 v[232:235], v194 offset:55296
	ds_read_b128 v[236:239], v194 offset:56320
	global_load_lds_dwordx4 v2, s[98:99]
	s_add_i32 m0, s26, 0x2000
	s_add_u32 s22, s22, 0x80080
	s_addc_u32 s23, s23, 0
	s_add_i32 s26, s49, s28
	global_load_lds_dwordx4 v156, s[98:99]
	s_mov_b32 m0, s26
	s_nop 0
	global_load_lds_dwordx4 v2, s[22:23]
	s_add_i32 m0, s26, 0x2000
	s_nop 0
	global_load_lds_dwordx4 v156, s[22:23]
	s_mov_b32 m0, s44
	s_nop 0
	global_load_lds_dwordx4 v160, s[100:101]
	s_mov_b32 m0, s45
	s_nop 0
	global_load_lds_dwordx4 v158, s[100:101]
	s_waitcnt vmcnt(8)
	s_waitcnt lgkmcnt(0)
	s_setprio 1
	s_barrier
	v_mfma_f32_16x16x32_bf16 v[80:83], v[148:151], v[204:207], v[80:83]
	v_mfma_f32_16x16x32_bf16 v[72:75], v[172:175], v[204:207], v[72:75]
	v_mfma_f32_16x16x32_bf16 v[64:67], v[148:151], v[216:219], v[64:67]
	v_mfma_f32_16x16x32_bf16 v[56:59], v[172:175], v[216:219], v[56:59]
	v_mfma_f32_16x16x32_bf16 v[48:51], v[148:151], v[224:227], v[48:51]
	v_mfma_f32_16x16x32_bf16 v[40:43], v[172:175], v[224:227], v[40:43]
	v_mfma_f32_16x16x32_bf16 v[32:35], v[148:151], v[232:235], v[32:35]
	v_mfma_f32_16x16x32_bf16 v[24:27], v[172:175], v[232:235], v[24:27]
	v_mfma_f32_16x16x32_bf16 v[80:83], v[152:155], v[212:215], v[80:83]
	v_mfma_f32_16x16x32_bf16 v[72:75], v[176:179], v[212:215], v[72:75]
	v_mfma_f32_16x16x32_bf16 v[64:67], v[152:155], v[220:223], v[64:67]
	v_mfma_f32_16x16x32_bf16 v[56:59], v[176:179], v[220:223], v[56:59]
	v_mfma_f32_16x16x32_bf16 v[48:51], v[152:155], v[228:231], v[48:51]
	v_mfma_f32_16x16x32_bf16 v[40:43], v[176:179], v[228:231], v[40:43]
	v_mfma_f32_16x16x32_bf16 v[32:35], v[152:155], v[236:239], v[32:35]
	v_mfma_f32_16x16x32_bf16 v[24:27], v[176:179], v[236:239], v[24:27]
	v_mfma_f32_16x16x32_bf16 v[76:79], v[180:183], v[204:207], v[76:79]
	v_mfma_f32_16x16x32_bf16 v[68:71], v[196:199], v[204:207], v[68:71]
	v_mfma_f32_16x16x32_bf16 v[60:63], v[180:183], v[216:219], v[60:63]
	v_mfma_f32_16x16x32_bf16 v[52:55], v[196:199], v[216:219], v[52:55]
	v_mfma_f32_16x16x32_bf16 v[44:47], v[180:183], v[224:227], v[44:47]
	v_mfma_f32_16x16x32_bf16 v[36:39], v[196:199], v[224:227], v[36:39]
	v_mfma_f32_16x16x32_bf16 v[28:31], v[180:183], v[232:235], v[28:31]
	v_mfma_f32_16x16x32_bf16 v[20:23], v[196:199], v[232:235], v[20:23]
	v_mfma_f32_16x16x32_bf16 v[76:79], v[184:187], v[212:215], v[76:79]
	v_mfma_f32_16x16x32_bf16 v[68:71], v[200:203], v[212:215], v[68:71]
	v_mfma_f32_16x16x32_bf16 v[60:63], v[184:187], v[220:223], v[60:63]
	v_mfma_f32_16x16x32_bf16 v[52:55], v[200:203], v[220:223], v[52:55]
	v_mfma_f32_16x16x32_bf16 v[44:47], v[184:187], v[228:231], v[44:47]
	v_mfma_f32_16x16x32_bf16 v[36:39], v[200:203], v[228:231], v[36:39]
	v_mfma_f32_16x16x32_bf16 v[28:31], v[184:187], v[236:239], v[28:31]
	v_mfma_f32_16x16x32_bf16 v[20:23], v[200:203], v[236:239], v[20:23]
	s_barrier
	s_setprio 0
	s_add_i32 s35, s35, 2
	s_add_u32 s2, s2, 0x1000
	s_addc_u32 s3, s3, 0
	s_add_u32 s33, s33, 0x100
	s_addc_u32 s34, s34, 0
	s_cmp_gt_u32 s35, 27
	s_cbranch_scc0 .LBB0_256
.Llast_256:
	s_add_u32 s22, s2, 0xfff80800
	s_addc_u32 s23, s3, -1
	s_add_i32 s48, 0, 0x10000
	s_cmp_eq_u32 s35, 28
	s_cselect_b32 s27, s8, s23
	s_cselect_b32 s26, s9, s22
	s_cselect_b32 s23, s15, s34
	s_cselect_b32 s22, s17, s33
	s_add_i32 s50, 0, 0x14000
	v_add_u32_e32 v176, s48, v191
	v_add_u32_e32 v188, s50, v191
	ds_read_b128 v[148:151], v176
	ds_read_b128 v[152:155], v176 offset:1024
	ds_read_b128 v[172:175], v176 offset:2048
	ds_read_b128 v[176:179], v176 offset:3072
	ds_read_b128 v[180:183], v188
	ds_read_b128 v[184:187], v188 offset:1024
	ds_read_b128 v[196:199], v188 offset:2048
	ds_read_b128 v[200:203], v188 offset:3072
	s_add_i32 m0, s39, 0xc000
	ds_read_b128 v[204:207], v194
	ds_read_b128 v[212:215], v194 offset:1024
	ds_read_b128 v[216:219], v194 offset:2048
	ds_read_b128 v[220:223], v194 offset:3072
	ds_read_b128 v[224:227], v194 offset:4096
	ds_read_b128 v[228:231], v194 offset:5120
	ds_read_b128 v[232:235], v194 offset:6144
	ds_read_b128 v[236:239], v194 offset:7168
	global_load_lds_dwordx4 v168, s[2:3]
	s_add_i32 m0, s39, 0xe000
	s_nop 0
	global_load_lds_dwordx4 v170, s[2:3]
	s_waitcnt vmcnt(8)
	s_waitcnt lgkmcnt(0)
	s_setprio 1
	s_barrier
	v_mfma_f32_16x16x32_bf16 v[144:147], v[148:151], v[204:207], v[144:147]
	v_mfma_f32_16x16x32_bf16 v[136:139], v[172:175], v[204:207], v[136:139]
	v_mfma_f32_16x16x32_bf16 v[128:131], v[148:151], v[216:219], v[128:131]
	v_mfma_f32_16x16x32_bf16 v[120:123], v[172:175], v[216:219], v[120:123]
	v_mfma_f32_16x16x32_bf16 v[112:115], v[148:151], v[224:227], v[112:115]
	v_mfma_f32_16x16x32_bf16 v[104:107], v[172:175], v[224:227], v[104:107]
	v_mfma_f32_16x16x32_bf16 v[96:99], v[148:151], v[232:235], v[96:99]
	v_mfma_f32_16x16x32_bf16 v[88:91], v[172:175], v[232:235], v[88:91]
	v_mfma_f32_16x16x32_bf16 v[144:147], v[152:155], v[212:215], v[144:147]
	v_mfma_f32_16x16x32_bf16 v[136:139], v[176:179], v[212:215], v[136:139]
	v_mfma_f32_16x16x32_bf16 v[128:131], v[152:155], v[220:223], v[128:131]
	v_mfma_f32_16x16x32_bf16 v[120:123], v[176:179], v[220:223], v[120:123]
	v_mfma_f32_16x16x32_bf16 v[112:115], v[152:155], v[228:231], v[112:115]
	v_mfma_f32_16x16x32_bf16 v[104:107], v[176:179], v[228:231], v[104:107]
	v_mfma_f32_16x16x32_bf16 v[96:99], v[152:155], v[236:239], v[96:99]
	v_mfma_f32_16x16x32_bf16 v[88:91], v[176:179], v[236:239], v[88:91]
	v_mfma_f32_16x16x32_bf16 v[140:143], v[180:183], v[204:207], v[140:143]
	v_mfma_f32_16x16x32_bf16 v[132:135], v[196:199], v[204:207], v[132:135]
	v_mfma_f32_16x16x32_bf16 v[124:127], v[180:183], v[216:219], v[124:127]
	v_mfma_f32_16x16x32_bf16 v[116:119], v[196:199], v[216:219], v[116:119]
	v_mfma_f32_16x16x32_bf16 v[108:111], v[180:183], v[224:227], v[108:111]
	v_mfma_f32_16x16x32_bf16 v[100:103], v[196:199], v[224:227], v[100:103]
	v_mfma_f32_16x16x32_bf16 v[92:95], v[180:183], v[232:235], v[92:95]
	v_mfma_f32_16x16x32_bf16 v[84:87], v[196:199], v[232:235], v[84:87]
	v_mfma_f32_16x16x32_bf16 v[140:143], v[184:187], v[212:215], v[140:143]
	v_mfma_f32_16x16x32_bf16 v[132:135], v[200:203], v[212:215], v[132:135]
	v_mfma_f32_16x16x32_bf16 v[124:127], v[184:187], v[220:223], v[124:127]
	v_mfma_f32_16x16x32_bf16 v[116:119], v[200:203], v[220:223], v[116:119]
	v_mfma_f32_16x16x32_bf16 v[108:111], v[184:187], v[228:231], v[108:111]
	v_mfma_f32_16x16x32_bf16 v[100:103], v[200:203], v[228:231], v[100:103]
	v_mfma_f32_16x16x32_bf16 v[92:95], v[184:187], v[236:239], v[92:95]
	v_mfma_f32_16x16x32_bf16 v[84:87], v[200:203], v[236:239], v[84:87]
	s_barrier
	s_setprio 0
	s_add_i32 s48, s48, s28
	s_add_u32 s98, s22, 0x80
	s_addc_u32 s99, s23, 0
	s_add_u32 s100, s26, 0x800
	s_addc_u32 s101, s27, 0
	s_mov_b32 m0, s48
	ds_read_b128 v[204:207], v194 offset:16384
	ds_read_b128 v[212:215], v194 offset:17408
	ds_read_b128 v[216:219], v194 offset:18432
	ds_read_b128 v[220:223], v194 offset:19456
	ds_read_b128 v[224:227], v194 offset:20480
	ds_read_b128 v[228:231], v194 offset:21504
	ds_read_b128 v[232:235], v194 offset:22528
	ds_read_b128 v[236:239], v194 offset:23552
	global_load_lds_dwordx4 v2, s[22:23]
	s_add_i32 m0, s48, 0x2000
	s_add_u32 s48, s22, 0x80000
	s_addc_u32 s49, s23, 0
	s_add_i32 s50, s50, s28
	global_load_lds_dwordx4 v156, s[22:23]
	s_mov_b32 m0, s50
	s_nop 0
	global_load_lds_dwordx4 v2, s[48:49]
	s_add_i32 m0, s50, 0x2000
	s_nop 0
	global_load_lds_dwordx4 v156, s[48:49]
	s_mov_b32 m0, s39
	s_nop 0
	global_load_lds_dwordx4 v160, s[26:27]
	s_mov_b32 m0, s41
	s_nop 0
	global_load_lds_dwordx4 v158, s[26:27]
	s_waitcnt vmcnt(8)
	s_waitcnt lgkmcnt(0)
	s_setprio 1
	s_barrier
	v_mfma_f32_16x16x32_bf16 v[80:83], v[148:151], v[204:207], v[80:83]
	v_mfma_f32_16x16x32_bf16 v[72:75], v[172:175], v[204:207], v[72:75]
	v_mfma_f32_16x16x32_bf16 v[64:67], v[148:151], v[216:219], v[64:67]
	v_mfma_f32_16x16x32_bf16 v[56:59], v[172:175], v[216:219], v[56:59]
	v_mfma_f32_16x16x32_bf16 v[48:51], v[148:151], v[224:227], v[48:51]
	v_mfma_f32_16x16x32_bf16 v[40:43], v[172:175], v[224:227], v[40:43]
	v_mfma_f32_16x16x32_bf16 v[32:35], v[148:151], v[232:235], v[32:35]
	v_mfma_f32_16x16x32_bf16 v[24:27], v[172:175], v[232:235], v[24:27]
	v_mfma_f32_16x16x32_bf16 v[80:83], v[152:155], v[212:215], v[80:83]
	v_mfma_f32_16x16x32_bf16 v[72:75], v[176:179], v[212:215], v[72:75]
	v_mfma_f32_16x16x32_bf16 v[64:67], v[152:155], v[220:223], v[64:67]
	v_mfma_f32_16x16x32_bf16 v[56:59], v[176:179], v[220:223], v[56:59]
	v_mfma_f32_16x16x32_bf16 v[48:51], v[152:155], v[228:231], v[48:51]
	v_mfma_f32_16x16x32_bf16 v[40:43], v[176:179], v[228:231], v[40:43]
	v_mfma_f32_16x16x32_bf16 v[32:35], v[152:155], v[236:239], v[32:35]
	v_mfma_f32_16x16x32_bf16 v[24:27], v[176:179], v[236:239], v[24:27]
	v_mfma_f32_16x16x32_bf16 v[76:79], v[180:183], v[204:207], v[76:79]
	v_mfma_f32_16x16x32_bf16 v[68:71], v[196:199], v[204:207], v[68:71]
	v_mfma_f32_16x16x32_bf16 v[60:63], v[180:183], v[216:219], v[60:63]
	v_mfma_f32_16x16x32_bf16 v[52:55], v[196:199], v[216:219], v[52:55]
	v_mfma_f32_16x16x32_bf16 v[44:47], v[180:183], v[224:227], v[44:47]
	v_mfma_f32_16x16x32_bf16 v[36:39], v[196:199], v[224:227], v[36:39]
	v_mfma_f32_16x16x32_bf16 v[28:31], v[180:183], v[232:235], v[28:31]
	v_mfma_f32_16x16x32_bf16 v[20:23], v[196:199], v[232:235], v[20:23]
	v_mfma_f32_16x16x32_bf16 v[76:79], v[184:187], v[212:215], v[76:79]
	v_mfma_f32_16x16x32_bf16 v[68:71], v[200:203], v[212:215], v[68:71]
	v_mfma_f32_16x16x32_bf16 v[60:63], v[184:187], v[220:223], v[60:63]
	v_mfma_f32_16x16x32_bf16 v[52:55], v[200:203], v[220:223], v[52:55]
	v_mfma_f32_16x16x32_bf16 v[44:47], v[184:187], v[228:231], v[44:47]
	v_mfma_f32_16x16x32_bf16 v[36:39], v[200:203], v[228:231], v[36:39]
	v_mfma_f32_16x16x32_bf16 v[28:31], v[184:187], v[236:239], v[28:31]
	v_mfma_f32_16x16x32_bf16 v[20:23], v[200:203], v[236:239], v[20:23]
	s_barrier
	s_setprio 0
	s_add_i32 s48, 0, 0x18000
	s_add_i32 s49, 0, 0x1c000
	v_add_u32_e32 v176, s48, v191
	v_add_u32_e32 v195, s49, v191
	ds_read_b128 v[148:151], v176
	ds_read_b128 v[152:155], v176 offset:1024
	ds_read_b128 v[172:175], v176 offset:2048
	ds_read_b128 v[176:179], v176 offset:3072
	ds_read_b128 v[180:183], v195
	ds_read_b128 v[184:187], v195 offset:1024
	ds_read_b128 v[196:199], v195 offset:2048
	ds_read_b128 v[200:203], v195 offset:3072
	s_add_u32 s26, s26, 0x80000
	s_addc_u32 s27, s27, 0
	s_mov_b32 m0, s42
	ds_read_b128 v[204:207], v194 offset:32768
	ds_read_b128 v[212:215], v194 offset:33792
	ds_read_b128 v[216:219], v194 offset:34816
	ds_read_b128 v[220:223], v194 offset:35840
	ds_read_b128 v[224:227], v194 offset:36864
	ds_read_b128 v[228:231], v194 offset:37888
	ds_read_b128 v[232:235], v194 offset:38912
	ds_read_b128 v[236:239], v194 offset:39936
	global_load_lds_dwordx4 v160, s[26:27]
	s_mov_b32 m0, s43
	s_nop 0
	global_load_lds_dwordx4 v158, s[26:27]
	s_waitcnt vmcnt(8)
	s_waitcnt lgkmcnt(0)
	s_setprio 1
	s_barrier
	v_mfma_f32_16x16x32_bf16 v[144:147], v[148:151], v[204:207], v[144:147]
	v_mfma_f32_16x16x32_bf16 v[136:139], v[172:175], v[204:207], v[136:139]
	v_mfma_f32_16x16x32_bf16 v[128:131], v[148:151], v[216:219], v[128:131]
	v_mfma_f32_16x16x32_bf16 v[120:123], v[172:175], v[216:219], v[120:123]
	v_mfma_f32_16x16x32_bf16 v[112:115], v[148:151], v[224:227], v[112:115]
	v_mfma_f32_16x16x32_bf16 v[104:107], v[172:175], v[224:227], v[104:107]
	v_mfma_f32_16x16x32_bf16 v[96:99], v[148:151], v[232:235], v[96:99]
	v_mfma_f32_16x16x32_bf16 v[88:91], v[172:175], v[232:235], v[88:91]
	v_mfma_f32_16x16x32_bf16 v[144:147], v[152:155], v[212:215], v[144:147]
	v_mfma_f32_16x16x32_bf16 v[136:139], v[176:179], v[212:215], v[136:139]
	v_mfma_f32_16x16x32_bf16 v[128:131], v[152:155], v[220:223], v[128:131]
	v_mfma_f32_16x16x32_bf16 v[120:123], v[176:179], v[220:223], v[120:123]
	v_mfma_f32_16x16x32_bf16 v[112:115], v[152:155], v[228:231], v[112:115]
	v_mfma_f32_16x16x32_bf16 v[104:107], v[176:179], v[228:231], v[104:107]
	v_mfma_f32_16x16x32_bf16 v[96:99], v[152:155], v[236:239], v[96:99]
	v_mfma_f32_16x16x32_bf16 v[88:91], v[176:179], v[236:239], v[88:91]
	v_mfma_f32_16x16x32_bf16 v[140:143], v[180:183], v[204:207], v[140:143]
	v_mfma_f32_16x16x32_bf16 v[132:135], v[196:199], v[204:207], v[132:135]
	v_mfma_f32_16x16x32_bf16 v[124:127], v[180:183], v[216:219], v[124:127]
	v_mfma_f32_16x16x32_bf16 v[116:119], v[196:199], v[216:219], v[116:119]
	v_mfma_f32_16x16x32_bf16 v[108:111], v[180:183], v[224:227], v[108:111]
	v_mfma_f32_16x16x32_bf16 v[100:103], v[196:199], v[224:227], v[100:103]
	v_mfma_f32_16x16x32_bf16 v[92:95], v[180:183], v[232:235], v[92:95]
	v_mfma_f32_16x16x32_bf16 v[84:87], v[196:199], v[232:235], v[84:87]
	v_mfma_f32_16x16x32_bf16 v[140:143], v[184:187], v[212:215], v[140:143]
	v_mfma_f32_16x16x32_bf16 v[132:135], v[200:203], v[212:215], v[132:135]
	v_mfma_f32_16x16x32_bf16 v[124:127], v[184:187], v[220:223], v[124:127]
	v_mfma_f32_16x16x32_bf16 v[116:119], v[200:203], v[220:223], v[116:119]
	v_mfma_f32_16x16x32_bf16 v[108:111], v[184:187], v[228:231], v[108:111]
	v_mfma_f32_16x16x32_bf16 v[100:103], v[200:203], v[228:231], v[100:103]
	v_mfma_f32_16x16x32_bf16 v[92:95], v[184:187], v[236:239], v[92:95]
	v_mfma_f32_16x16x32_bf16 v[84:87], v[200:203], v[236:239], v[84:87]
	s_barrier
	s_setprio 0
	s_add_i32 s26, s48, s28
	s_mov_b32 m0, s26
	ds_read_b128 v[204:207], v194 offset:49152
	ds_read_b128 v[212:215], v194 offset:50176
	ds_read_b128 v[216:219], v194 offset:51200
	ds_read_b128 v[220:223], v194 offset:52224
	ds_read_b128 v[224:227], v194 offset:53248
	ds_read_b128 v[228:231], v194 offset:54272
	ds_read_b128 v[232:235], v194 offset:55296
	ds_read_b128 v[236:239], v194 offset:56320
	global_load_lds_dwordx4 v2, s[98:99]
	s_add_i32 m0, s26, 0x2000
	s_add_u32 s22, s22, 0x80080
	s_addc_u32 s23, s23, 0
	s_add_i32 s26, s49, s28
	global_load_lds_dwordx4 v156, s[98:99]
	s_mov_b32 m0, s26
	s_nop 0
	global_load_lds_dwordx4 v2, s[22:23]
	s_add_i32 m0, s26, 0x2000
	s_nop 0
	global_load_lds_dwordx4 v156, s[22:23]
	s_mov_b32 m0, s44
	s_nop 0
	global_load_lds_dwordx4 v160, s[100:101]
	s_mov_b32 m0, s45
	s_nop 0
	global_load_lds_dwordx4 v158, s[100:101]
	s_waitcnt vmcnt(8)
	s_waitcnt lgkmcnt(0)
	s_setprio 1
	s_barrier
	v_mfma_f32_16x16x32_bf16 v[80:83], v[148:151], v[204:207], v[80:83]
	v_mfma_f32_16x16x32_bf16 v[72:75], v[172:175], v[204:207], v[72:75]
	v_mfma_f32_16x16x32_bf16 v[64:67], v[148:151], v[216:219], v[64:67]
	v_mfma_f32_16x16x32_bf16 v[56:59], v[172:175], v[216:219], v[56:59]
	v_mfma_f32_16x16x32_bf16 v[48:51], v[148:151], v[224:227], v[48:51]
	v_mfma_f32_16x16x32_bf16 v[40:43], v[172:175], v[224:227], v[40:43]
	v_mfma_f32_16x16x32_bf16 v[32:35], v[148:151], v[232:235], v[32:35]
	v_mfma_f32_16x16x32_bf16 v[24:27], v[172:175], v[232:235], v[24:27]
	v_mfma_f32_16x16x32_bf16 v[80:83], v[152:155], v[212:215], v[80:83]
	v_mfma_f32_16x16x32_bf16 v[72:75], v[176:179], v[212:215], v[72:75]
	v_mfma_f32_16x16x32_bf16 v[64:67], v[152:155], v[220:223], v[64:67]
	v_mfma_f32_16x16x32_bf16 v[56:59], v[176:179], v[220:223], v[56:59]
	v_mfma_f32_16x16x32_bf16 v[48:51], v[152:155], v[228:231], v[48:51]
	v_mfma_f32_16x16x32_bf16 v[40:43], v[176:179], v[228:231], v[40:43]
	v_mfma_f32_16x16x32_bf16 v[32:35], v[152:155], v[236:239], v[32:35]
	v_mfma_f32_16x16x32_bf16 v[24:27], v[176:179], v[236:239], v[24:27]
	v_mfma_f32_16x16x32_bf16 v[76:79], v[180:183], v[204:207], v[76:79]
	v_mfma_f32_16x16x32_bf16 v[68:71], v[196:199], v[204:207], v[68:71]
	v_mfma_f32_16x16x32_bf16 v[60:63], v[180:183], v[216:219], v[60:63]
	v_mfma_f32_16x16x32_bf16 v[52:55], v[196:199], v[216:219], v[52:55]
	v_mfma_f32_16x16x32_bf16 v[44:47], v[180:183], v[224:227], v[44:47]
	v_mfma_f32_16x16x32_bf16 v[36:39], v[196:199], v[224:227], v[36:39]
	v_mfma_f32_16x16x32_bf16 v[28:31], v[180:183], v[232:235], v[28:31]
	v_mfma_f32_16x16x32_bf16 v[20:23], v[196:199], v[232:235], v[20:23]
	v_mfma_f32_16x16x32_bf16 v[76:79], v[184:187], v[212:215], v[76:79]
	v_mfma_f32_16x16x32_bf16 v[68:71], v[200:203], v[212:215], v[68:71]
	v_mfma_f32_16x16x32_bf16 v[60:63], v[184:187], v[220:223], v[60:63]
	v_mfma_f32_16x16x32_bf16 v[52:55], v[200:203], v[220:223], v[52:55]
	v_mfma_f32_16x16x32_bf16 v[44:47], v[184:187], v[228:231], v[44:47]
	v_mfma_f32_16x16x32_bf16 v[36:39], v[200:203], v[228:231], v[36:39]
	v_mfma_f32_16x16x32_bf16 v[28:31], v[184:187], v[236:239], v[28:31]
	v_mfma_f32_16x16x32_bf16 v[20:23], v[200:203], v[236:239], v[20:23]
	s_setprio 0
	s_add_i32 s35, s35, 2
	s_add_u32 s2, s2, 0x1000
	s_addc_u32 s3, s3, 0
	s_add_u32 s33, s33, 0x100
	s_addc_u32 s34, s34, 0

.LBB0_488:
	s_ashr_i32 s17, s16, 31
	s_lshl_b64 s[8:9], s[16:17], 20
	v_readlane_b32 s18, v254, 39
	v_readlane_b32 s19, v254, 40
	s_add_u32 s18, s18, s8
	s_addc_u32 s19, s19, s9
	s_and_b64 s[8:9], s[36:37], exec
	s_cselect_b32 s3, s19, s23
	s_cselect_b32 s6, s18, s22
	s_ashr_i32 s15, s14, 31
	s_lshl_b64 s[8:9], s[14:15], 20
	s_add_u32 s20, s28, s8
	s_addc_u32 s21, s29, s9
	s_and_b64 s[8:9], s[36:37], exec
	s_cselect_b32 s8, s21, s27
	s_cselect_b32 s9, s20, s26
	s_add_u32 s22, s22, 0x80800
	s_addc_u32 s23, s23, 0
	s_add_u32 s15, s26, 0x100
	s_addc_u32 s17, s27, 0
	s_mov_b32 s33, -2
	s_add_u32 s26, s22, 0xfff80800
	s_addc_u32 s27, s23, -1
	s_add_i32 s34, 0, 0x10000
	s_cmp_eq_u32 s33, 28
	s_cselect_b32 s39, s3, s27
	s_cselect_b32 s38, s6, s26
	s_cselect_b32 s27, s8, s17
	s_cselect_b32 s26, s9, s15
	s_add_i32 s53, 0, 0x14000
	v_add_u32_e32 v144, s34, v168
	v_add_u32_e32 v160, s53, v168
	ds_read_b128 v[4:7], v144
	ds_read_b128 v[8:11], v144 offset:1024
	ds_read_b128 v[140:143], v144 offset:2048
	ds_read_b128 v[144:147], v144 offset:3072
	ds_read_b128 v[172:175], v160
	ds_read_b128 v[176:179], v160 offset:1024
	ds_read_b128 v[180:183], v160 offset:2048
	ds_read_b128 v[184:187], v160 offset:3072
	s_add_i32 m0, s13, 0xc000
	ds_read_b128 v[188:191], v170
	ds_read_b128 v[192:195], v170 offset:1024
	ds_read_b128 v[196:199], v170 offset:2048
	ds_read_b128 v[200:203], v170 offset:3072
	ds_read_b128 v[204:207], v170 offset:4096
	ds_read_b128 v[212:215], v170 offset:5120
	ds_read_b128 v[216:219], v170 offset:6144
	ds_read_b128 v[220:223], v170 offset:7168
	global_load_lds_dwordx4 v156, s[22:23]
	s_add_i32 m0, s13, 0xe000
	s_nop 0
	global_load_lds_dwordx4 v158, s[22:23]
	s_waitcnt vmcnt(8)
	s_waitcnt lgkmcnt(0)
	s_setprio 1
	s_barrier
	v_mfma_f32_16x16x32_bf16 v[136:139], v[4:7], v[188:191], 0
	v_mfma_f32_16x16x32_bf16 v[132:135], v[140:143], v[188:191], 0
	v_mfma_f32_16x16x32_bf16 v[128:131], v[4:7], v[196:199], 0
	v_mfma_f32_16x16x32_bf16 v[120:123], v[140:143], v[196:199], 0
	v_mfma_f32_16x16x32_bf16 v[112:115], v[4:7], v[204:207], 0
	v_mfma_f32_16x16x32_bf16 v[104:107], v[140:143], v[204:207], 0
	v_mfma_f32_16x16x32_bf16 v[96:99], v[4:7], v[216:219], 0
	v_mfma_f32_16x16x32_bf16 v[88:91], v[140:143], v[216:219], 0
	v_mfma_f32_16x16x32_bf16 v[136:139], v[8:11], v[192:195], v[136:139]
	v_mfma_f32_16x16x32_bf16 v[132:135], v[144:147], v[192:195], v[132:135]
	v_mfma_f32_16x16x32_bf16 v[128:131], v[8:11], v[200:203], v[128:131]
	v_mfma_f32_16x16x32_bf16 v[120:123], v[144:147], v[200:203], v[120:123]
	v_mfma_f32_16x16x32_bf16 v[112:115], v[8:11], v[212:215], v[112:115]
	v_mfma_f32_16x16x32_bf16 v[104:107], v[144:147], v[212:215], v[104:107]
	v_mfma_f32_16x16x32_bf16 v[96:99], v[8:11], v[220:223], v[96:99]
	v_mfma_f32_16x16x32_bf16 v[88:91], v[144:147], v[220:223], v[88:91]
	v_mfma_f32_16x16x32_bf16 v[124:127], v[172:175], v[188:191], 0
	v_mfma_f32_16x16x32_bf16 v[116:119], v[180:183], v[188:191], 0
	v_mfma_f32_16x16x32_bf16 v[108:111], v[172:175], v[196:199], 0
	v_mfma_f32_16x16x32_bf16 v[100:103], v[180:183], v[196:199], 0
	v_mfma_f32_16x16x32_bf16 v[92:95], v[172:175], v[204:207], 0
	v_mfma_f32_16x16x32_bf16 v[84:87], v[180:183], v[204:207], 0
	v_mfma_f32_16x16x32_bf16 v[80:83], v[172:175], v[216:219], 0
	v_mfma_f32_16x16x32_bf16 v[76:79], v[180:183], v[216:219], 0
	v_mfma_f32_16x16x32_bf16 v[124:127], v[176:179], v[192:195], v[124:127]
	v_mfma_f32_16x16x32_bf16 v[116:119], v[184:187], v[192:195], v[116:119]
	v_mfma_f32_16x16x32_bf16 v[108:111], v[176:179], v[200:203], v[108:111]
	v_mfma_f32_16x16x32_bf16 v[100:103], v[184:187], v[200:203], v[100:103]
	v_mfma_f32_16x16x32_bf16 v[92:95], v[176:179], v[212:215], v[92:95]
	v_mfma_f32_16x16x32_bf16 v[84:87], v[184:187], v[212:215], v[84:87]
	v_mfma_f32_16x16x32_bf16 v[80:83], v[176:179], v[220:223], v[80:83]
	v_mfma_f32_16x16x32_bf16 v[76:79], v[184:187], v[220:223], v[76:79]
	s_barrier
	s_setprio 0
	s_add_i32 s34, s34, s7
	s_add_u32 s98, s26, 0x80
	s_addc_u32 s99, s27, 0
	s_add_u32 s100, s38, 0x800
	s_addc_u32 s101, s39, 0
	s_mov_b32 m0, s34
	ds_read_b128 v[188:191], v170 offset:16384
	ds_read_b128 v[192:195], v170 offset:17408
	ds_read_b128 v[196:199], v170 offset:18432
	ds_read_b128 v[200:203], v170 offset:19456
	ds_read_b128 v[204:207], v170 offset:20480
	ds_read_b128 v[212:215], v170 offset:21504
	ds_read_b128 v[216:219], v170 offset:22528
	ds_read_b128 v[220:223], v170 offset:23552
	global_load_lds_dwordx4 v2, s[26:27]
	s_add_i32 m0, s34, 0x2000
	s_add_u32 s34, s26, 0x80000
	s_addc_u32 s35, s27, 0
	s_add_i32 s53, s53, s7
	global_load_lds_dwordx4 v148, s[26:27]
	s_mov_b32 m0, s53
	s_nop 0
	global_load_lds_dwordx4 v2, s[34:35]
	s_add_i32 m0, s53, 0x2000
	s_nop 0
	global_load_lds_dwordx4 v148, s[34:35]
	s_mov_b32 m0, s13
	s_nop 0
	global_load_lds_dwordx4 v152, s[38:39]
	s_mov_b32 m0, s46
	s_nop 0
	global_load_lds_dwordx4 v150, s[38:39]
	s_waitcnt vmcnt(8)
	s_waitcnt lgkmcnt(0)
	s_setprio 1
	s_barrier
	v_mfma_f32_16x16x32_bf16 v[72:75], v[4:7], v[188:191], 0
	v_mfma_f32_16x16x32_bf16 v[68:71], v[140:143], v[188:191], 0
	v_mfma_f32_16x16x32_bf16 v[64:67], v[4:7], v[196:199], 0
	v_mfma_f32_16x16x32_bf16 v[56:59], v[140:143], v[196:199], 0
	v_mfma_f32_16x16x32_bf16 v[48:51], v[4:7], v[204:207], 0
	v_mfma_f32_16x16x32_bf16 v[40:43], v[140:143], v[204:207], 0
	v_mfma_f32_16x16x32_bf16 v[4:7], v[4:7], v[216:219], 0
	v_mfma_f32_16x16x32_bf16 v[72:75], v[8:11], v[192:195], v[72:75]
	v_mfma_f32_16x16x32_bf16 v[68:71], v[144:147], v[192:195], v[68:71]
	v_mfma_f32_16x16x32_bf16 v[64:67], v[8:11], v[200:203], v[64:67]
	v_mfma_f32_16x16x32_bf16 v[56:59], v[144:147], v[200:203], v[56:59]
	v_mfma_f32_16x16x32_bf16 v[48:51], v[8:11], v[212:215], v[48:51]
	v_mfma_f32_16x16x32_bf16 v[40:43], v[144:147], v[212:215], v[40:43]
	v_mfma_f32_16x16x32_bf16 v[4:7], v[8:11], v[220:223], v[4:7]
	v_mfma_f32_16x16x32_bf16 v[8:11], v[140:143], v[216:219], 0
	v_mfma_f32_16x16x32_bf16 v[8:11], v[144:147], v[220:223], v[8:11]
	v_mfma_f32_16x16x32_bf16 v[24:27], v[172:175], v[188:191], 0
	v_mfma_f32_16x16x32_bf16 v[60:63], v[176:179], v[192:195], v[24:27]
	v_mfma_f32_16x16x32_bf16 v[24:27], v[180:183], v[188:191], 0
	v_mfma_f32_16x16x32_bf16 v[52:55], v[184:187], v[192:195], v[24:27]
	v_mfma_f32_16x16x32_bf16 v[24:27], v[172:175], v[196:199], 0
	v_mfma_f32_16x16x32_bf16 v[44:47], v[176:179], v[200:203], v[24:27]
	v_mfma_f32_16x16x32_bf16 v[24:27], v[180:183], v[196:199], 0
	v_mfma_f32_16x16x32_bf16 v[36:39], v[184:187], v[200:203], v[24:27]
	v_mfma_f32_16x16x32_bf16 v[24:27], v[172:175], v[204:207], 0
	v_mfma_f32_16x16x32_bf16 v[20:23], v[180:183], v[204:207], 0
	v_mfma_f32_16x16x32_bf16 v[16:19], v[172:175], v[216:219], 0
	v_mfma_f32_16x16x32_bf16 v[12:15], v[180:183], v[216:219], 0
	v_mfma_f32_16x16x32_bf16 v[28:31], v[176:179], v[212:215], v[24:27]
	v_mfma_f32_16x16x32_bf16 v[20:23], v[184:187], v[212:215], v[20:23]
	v_mfma_f32_16x16x32_bf16 v[16:19], v[176:179], v[220:223], v[16:19]
	v_mfma_f32_16x16x32_bf16 v[12:15], v[184:187], v[220:223], v[12:15]
	s_barrier
	s_setprio 0
	s_add_i32 s53, 0, 0x18000
	s_add_i32 s54, 0, 0x1c000
	v_add_u32_e32 v144, s53, v168
	v_add_u32_e32 v171, s54, v168
	ds_read_b128 v[24:27], v144
	ds_read_b128 v[32:35], v144 offset:1024
	ds_read_b128 v[140:143], v144 offset:2048
	ds_read_b128 v[144:147], v144 offset:3072
	ds_read_b128 v[172:175], v171
	ds_read_b128 v[176:179], v171 offset:1024
	ds_read_b128 v[180:183], v171 offset:2048
	ds_read_b128 v[184:187], v171 offset:3072
	s_add_u32 s34, s38, 0x80000
	s_addc_u32 s35, s39, 0
	s_mov_b32 m0, s47
	ds_read_b128 v[188:191], v170 offset:32768
	ds_read_b128 v[192:195], v170 offset:33792
	ds_read_b128 v[196:199], v170 offset:34816
	ds_read_b128 v[200:203], v170 offset:35840
	ds_read_b128 v[204:207], v170 offset:36864
	ds_read_b128 v[212:215], v170 offset:37888
	ds_read_b128 v[216:219], v170 offset:38912
	ds_read_b128 v[220:223], v170 offset:39936
	global_load_lds_dwordx4 v152, s[34:35]
	s_mov_b32 m0, s48
	s_nop 0
	global_load_lds_dwordx4 v150, s[34:35]
	s_waitcnt vmcnt(8)
	s_waitcnt lgkmcnt(0)
	s_setprio 1
	s_barrier
	v_mfma_f32_16x16x32_bf16 v[136:139], v[24:27], v[188:191], v[136:139]
	v_mfma_f32_16x16x32_bf16 v[132:135], v[140:143], v[188:191], v[132:135]
	v_mfma_f32_16x16x32_bf16 v[128:131], v[24:27], v[196:199], v[128:131]
	v_mfma_f32_16x16x32_bf16 v[120:123], v[140:143], v[196:199], v[120:123]
	v_mfma_f32_16x16x32_bf16 v[112:115], v[24:27], v[204:207], v[112:115]
	v_mfma_f32_16x16x32_bf16 v[104:107], v[140:143], v[204:207], v[104:107]
	v_mfma_f32_16x16x32_bf16 v[96:99], v[24:27], v[216:219], v[96:99]
	v_mfma_f32_16x16x32_bf16 v[88:91], v[140:143], v[216:219], v[88:91]
	v_mfma_f32_16x16x32_bf16 v[136:139], v[32:35], v[192:195], v[136:139]
	v_mfma_f32_16x16x32_bf16 v[132:135], v[144:147], v[192:195], v[132:135]
	v_mfma_f32_16x16x32_bf16 v[128:131], v[32:35], v[200:203], v[128:131]
	v_mfma_f32_16x16x32_bf16 v[120:123], v[144:147], v[200:203], v[120:123]
	v_mfma_f32_16x16x32_bf16 v[112:115], v[32:35], v[212:215], v[112:115]
	v_mfma_f32_16x16x32_bf16 v[104:107], v[144:147], v[212:215], v[104:107]
	v_mfma_f32_16x16x32_bf16 v[96:99], v[32:35], v[220:223], v[96:99]
	v_mfma_f32_16x16x32_bf16 v[88:91], v[144:147], v[220:223], v[88:91]
	v_mfma_f32_16x16x32_bf16 v[124:127], v[172:175], v[188:191], v[124:127]
	v_mfma_f32_16x16x32_bf16 v[116:119], v[180:183], v[188:191], v[116:119]
	v_mfma_f32_16x16x32_bf16 v[108:111], v[172:175], v[196:199], v[108:111]
	v_mfma_f32_16x16x32_bf16 v[100:103], v[180:183], v[196:199], v[100:103]
	v_mfma_f32_16x16x32_bf16 v[92:95], v[172:175], v[204:207], v[92:95]
	v_mfma_f32_16x16x32_bf16 v[84:87], v[180:183], v[204:207], v[84:87]
	v_mfma_f32_16x16x32_bf16 v[80:83], v[172:175], v[216:219], v[80:83]
	v_mfma_f32_16x16x32_bf16 v[76:79], v[180:183], v[216:219], v[76:79]
	v_mfma_f32_16x16x32_bf16 v[124:127], v[176:179], v[192:195], v[124:127]
	v_mfma_f32_16x16x32_bf16 v[116:119], v[184:187], v[192:195], v[116:119]
	v_mfma_f32_16x16x32_bf16 v[108:111], v[176:179], v[200:203], v[108:111]
	v_mfma_f32_16x16x32_bf16 v[100:103], v[184:187], v[200:203], v[100:103]
	v_mfma_f32_16x16x32_bf16 v[92:95], v[176:179], v[212:215], v[92:95]
	v_mfma_f32_16x16x32_bf16 v[84:87], v[184:187], v[212:215], v[84:87]
	v_mfma_f32_16x16x32_bf16 v[80:83], v[176:179], v[220:223], v[80:83]
	v_mfma_f32_16x16x32_bf16 v[76:79], v[184:187], v[220:223], v[76:79]
	s_barrier
	s_setprio 0
	s_add_i32 s34, s53, s7
	s_mov_b32 m0, s34
	ds_read_b128 v[188:191], v170 offset:49152
	ds_read_b128 v[192:195], v170 offset:50176
	ds_read_b128 v[196:199], v170 offset:51200
	ds_read_b128 v[200:203], v170 offset:52224
	ds_read_b128 v[204:207], v170 offset:53248
	ds_read_b128 v[212:215], v170 offset:54272
	ds_read_b128 v[216:219], v170 offset:55296
	ds_read_b128 v[220:223], v170 offset:56320
	global_load_lds_dwordx4 v2, s[98:99]
	s_add_i32 m0, s34, 0x2000
	s_add_u32 s26, s26, 0x80080
	s_addc_u32 s27, s27, 0
	s_add_i32 s34, s54, s7
	global_load_lds_dwordx4 v148, s[98:99]
	s_mov_b32 m0, s34
	s_nop 0
	global_load_lds_dwordx4 v2, s[26:27]
	s_add_i32 m0, s34, 0x2000
	s_nop 0
	global_load_lds_dwordx4 v148, s[26:27]
	s_mov_b32 m0, s49
	s_nop 0
	global_load_lds_dwordx4 v152, s[100:101]
	s_mov_b32 m0, s50
	s_nop 0
	global_load_lds_dwordx4 v150, s[100:101]
	s_waitcnt vmcnt(8)
	s_waitcnt lgkmcnt(0)
	s_setprio 1
	s_barrier
	v_mfma_f32_16x16x32_bf16 v[72:75], v[24:27], v[188:191], v[72:75]
	v_mfma_f32_16x16x32_bf16 v[64:67], v[24:27], v[196:199], v[64:67]
	v_mfma_f32_16x16x32_bf16 v[48:51], v[24:27], v[204:207], v[48:51]
	v_mfma_f32_16x16x32_bf16 v[4:7], v[24:27], v[216:219], v[4:7]
	v_mfma_f32_16x16x32_bf16 v[72:75], v[32:35], v[192:195], v[72:75]
	v_mfma_f32_16x16x32_bf16 v[68:71], v[140:143], v[188:191], v[68:71]
	v_mfma_f32_16x16x32_bf16 v[64:67], v[32:35], v[200:203], v[64:67]
	v_mfma_f32_16x16x32_bf16 v[56:59], v[140:143], v[196:199], v[56:59]
	v_mfma_f32_16x16x32_bf16 v[48:51], v[32:35], v[212:215], v[48:51]
	v_mfma_f32_16x16x32_bf16 v[40:43], v[140:143], v[204:207], v[40:43]
	v_mfma_f32_16x16x32_bf16 v[32:35], v[32:35], v[220:223], v[4:7]
	v_mfma_f32_16x16x32_bf16 v[4:7], v[140:143], v[216:219], v[8:11]
	v_mfma_f32_16x16x32_bf16 v[68:71], v[144:147], v[192:195], v[68:71]
	v_mfma_f32_16x16x32_bf16 v[56:59], v[144:147], v[200:203], v[56:59]
	v_mfma_f32_16x16x32_bf16 v[40:43], v[144:147], v[212:215], v[40:43]
	v_mfma_f32_16x16x32_bf16 v[24:27], v[144:147], v[220:223], v[4:7]
	v_mfma_f32_16x16x32_bf16 v[4:7], v[172:175], v[188:191], v[60:63]
	v_mfma_f32_16x16x32_bf16 v[60:63], v[176:179], v[192:195], v[4:7]
	v_mfma_f32_16x16x32_bf16 v[4:7], v[180:183], v[188:191], v[52:55]
	v_mfma_f32_16x16x32_bf16 v[52:55], v[184:187], v[192:195], v[4:7]
	v_mfma_f32_16x16x32_bf16 v[4:7], v[172:175], v[196:199], v[44:47]
	v_mfma_f32_16x16x32_bf16 v[44:47], v[176:179], v[200:203], v[4:7]
	v_mfma_f32_16x16x32_bf16 v[4:7], v[180:183], v[196:199], v[36:39]
	v_mfma_f32_16x16x32_bf16 v[36:39], v[184:187], v[200:203], v[4:7]
	v_mfma_f32_16x16x32_bf16 v[4:7], v[172:175], v[204:207], v[28:31]
	v_mfma_f32_16x16x32_bf16 v[28:31], v[176:179], v[212:215], v[4:7]
	v_mfma_f32_16x16x32_bf16 v[4:7], v[180:183], v[204:207], v[20:23]
	v_mfma_f32_16x16x32_bf16 v[20:23], v[184:187], v[212:215], v[4:7]
	v_mfma_f32_16x16x32_bf16 v[4:7], v[172:175], v[216:219], v[16:19]
	v_mfma_f32_16x16x32_bf16 v[16:19], v[176:179], v[220:223], v[4:7]
	v_mfma_f32_16x16x32_bf16 v[4:7], v[180:183], v[216:219], v[12:15]
	v_mfma_f32_16x16x32_bf16 v[12:15], v[184:187], v[220:223], v[4:7]
	s_barrier
	s_setprio 0
	s_add_i32 s33, s33, 2
	s_add_u32 s22, s22, 0x1000
	s_addc_u32 s23, s23, 0
	s_add_u32 s15, s15, 0x100
	s_addc_u32 s17, s17, 0
	s_cmp_gt_u32 s33, 27
	s_cbranch_scc0 .LBB0_489
	s_branch .Llast_489
.LBB0_489:
	s_add_u32 s26, s22, 0xfff80800
	s_addc_u32 s27, s23, -1
	s_add_i32 s34, 0, 0x10000
	s_cmp_eq_u32 s33, 28
	s_cselect_b32 s39, s3, s27
	s_cselect_b32 s38, s6, s26
	s_cselect_b32 s27, s8, s17
	s_cselect_b32 s26, s9, s15
	s_add_i32 s53, 0, 0x14000
	v_add_u32_e32 v144, s34, v168
	v_add_u32_e32 v160, s53, v168
	ds_read_b128 v[4:7], v144
	ds_read_b128 v[8:11], v144 offset:1024
	ds_read_b128 v[140:143], v144 offset:2048
	ds_read_b128 v[144:147], v144 offset:3072
	ds_read_b128 v[172:175], v160
	ds_read_b128 v[176:179], v160 offset:1024
	ds_read_b128 v[180:183], v160 offset:2048
	ds_read_b128 v[184:187], v160 offset:3072
	s_add_i32 m0, s13, 0xc000
	ds_read_b128 v[188:191], v170
	ds_read_b128 v[192:195], v170 offset:1024
	ds_read_b128 v[196:199], v170 offset:2048
	ds_read_b128 v[200:203], v170 offset:3072
	ds_read_b128 v[204:207], v170 offset:4096
	ds_read_b128 v[212:215], v170 offset:5120
	ds_read_b128 v[216:219], v170 offset:6144
	ds_read_b128 v[220:223], v170 offset:7168
	global_load_lds_dwordx4 v156, s[22:23]
	s_add_i32 m0, s13, 0xe000
	s_nop 0
	global_load_lds_dwordx4 v158, s[22:23]
	s_waitcnt vmcnt(8)
	s_waitcnt lgkmcnt(0)
	s_setprio 1
	s_barrier
	v_mfma_f32_16x16x32_bf16 v[136:139], v[4:7], v[188:191], v[136:139]
	v_mfma_f32_16x16x32_bf16 v[132:135], v[140:143], v[188:191], v[132:135]
	v_mfma_f32_16x16x32_bf16 v[128:131], v[4:7], v[196:199], v[128:131]
	v_mfma_f32_16x16x32_bf16 v[120:123], v[140:143], v[196:199], v[120:123]
	v_mfma_f32_16x16x32_bf16 v[112:115], v[4:7], v[204:207], v[112:115]
	v_mfma_f32_16x16x32_bf16 v[104:107], v[140:143], v[204:207], v[104:107]
	v_mfma_f32_16x16x32_bf16 v[96:99], v[4:7], v[216:219], v[96:99]
	v_mfma_f32_16x16x32_bf16 v[88:91], v[140:143], v[216:219], v[88:91]
	v_mfma_f32_16x16x32_bf16 v[136:139], v[8:11], v[192:195], v[136:139]
	v_mfma_f32_16x16x32_bf16 v[132:135], v[144:147], v[192:195], v[132:135]
	v_mfma_f32_16x16x32_bf16 v[128:131], v[8:11], v[200:203], v[128:131]
	v_mfma_f32_16x16x32_bf16 v[120:123], v[144:147], v[200:203], v[120:123]
	v_mfma_f32_16x16x32_bf16 v[112:115], v[8:11], v[212:215], v[112:115]
	v_mfma_f32_16x16x32_bf16 v[104:107], v[144:147], v[212:215], v[104:107]
	v_mfma_f32_16x16x32_bf16 v[96:99], v[8:11], v[220:223], v[96:99]
	v_mfma_f32_16x16x32_bf16 v[88:91], v[144:147], v[220:223], v[88:91]
	v_mfma_f32_16x16x32_bf16 v[124:127], v[172:175], v[188:191], v[124:127]
	v_mfma_f32_16x16x32_bf16 v[116:119], v[180:183], v[188:191], v[116:119]
	v_mfma_f32_16x16x32_bf16 v[108:111], v[172:175], v[196:199], v[108:111]
	v_mfma_f32_16x16x32_bf16 v[100:103], v[180:183], v[196:199], v[100:103]
	v_mfma_f32_16x16x32_bf16 v[92:95], v[172:175], v[204:207], v[92:95]
	v_mfma_f32_16x16x32_bf16 v[84:87], v[180:183], v[204:207], v[84:87]
	v_mfma_f32_16x16x32_bf16 v[80:83], v[172:175], v[216:219], v[80:83]
	v_mfma_f32_16x16x32_bf16 v[76:79], v[180:183], v[216:219], v[76:79]
	v_mfma_f32_16x16x32_bf16 v[124:127], v[176:179], v[192:195], v[124:127]
	v_mfma_f32_16x16x32_bf16 v[116:119], v[184:187], v[192:195], v[116:119]
	v_mfma_f32_16x16x32_bf16 v[108:111], v[176:179], v[200:203], v[108:111]
	v_mfma_f32_16x16x32_bf16 v[100:103], v[184:187], v[200:203], v[100:103]
	v_mfma_f32_16x16x32_bf16 v[92:95], v[176:179], v[212:215], v[92:95]
	v_mfma_f32_16x16x32_bf16 v[84:87], v[184:187], v[212:215], v[84:87]
	v_mfma_f32_16x16x32_bf16 v[80:83], v[176:179], v[220:223], v[80:83]
	v_mfma_f32_16x16x32_bf16 v[76:79], v[184:187], v[220:223], v[76:79]
	s_barrier
	s_setprio 0
	s_add_i32 s34, s34, s7
	s_add_u32 s98, s26, 0x80
	s_addc_u32 s99, s27, 0
	s_add_u32 s100, s38, 0x800
	s_addc_u32 s101, s39, 0
	s_mov_b32 m0, s34
	ds_read_b128 v[188:191], v170 offset:16384
	ds_read_b128 v[192:195], v170 offset:17408
	ds_read_b128 v[196:199], v170 offset:18432
	ds_read_b128 v[200:203], v170 offset:19456
	ds_read_b128 v[204:207], v170 offset:20480
	ds_read_b128 v[212:215], v170 offset:21504
	ds_read_b128 v[216:219], v170 offset:22528
	ds_read_b128 v[220:223], v170 offset:23552
	global_load_lds_dwordx4 v2, s[26:27]
	s_add_i32 m0, s34, 0x2000
	s_add_u32 s34, s26, 0x80000
	s_addc_u32 s35, s27, 0
	s_add_i32 s53, s53, s7
	global_load_lds_dwordx4 v148, s[26:27]
	s_mov_b32 m0, s53
	s_nop 0
	global_load_lds_dwordx4 v2, s[34:35]
	s_add_i32 m0, s53, 0x2000
	s_nop 0
	global_load_lds_dwordx4 v148, s[34:35]
	s_mov_b32 m0, s13
	s_nop 0
	global_load_lds_dwordx4 v152, s[38:39]
	s_mov_b32 m0, s46
	s_nop 0
	global_load_lds_dwordx4 v150, s[38:39]
	s_waitcnt vmcnt(8)
	s_waitcnt lgkmcnt(0)
	s_setprio 1
	s_barrier
	v_mfma_f32_16x16x32_bf16 v[72:75], v[4:7], v[188:191], v[72:75]
	v_mfma_f32_16x16x32_bf16 v[68:71], v[140:143], v[188:191], v[68:71]
	v_mfma_f32_16x16x32_bf16 v[64:67], v[4:7], v[196:199], v[64:67]
	v_mfma_f32_16x16x32_bf16 v[56:59], v[140:143], v[196:199], v[56:59]
	v_mfma_f32_16x16x32_bf16 v[48:51], v[4:7], v[204:207], v[48:51]
	v_mfma_f32_16x16x32_bf16 v[40:43], v[140:143], v[204:207], v[40:43]
	v_mfma_f32_16x16x32_bf16 v[4:7], v[4:7], v[216:219], v[32:35]
	v_mfma_f32_16x16x32_bf16 v[72:75], v[8:11], v[192:195], v[72:75]
	v_mfma_f32_16x16x32_bf16 v[68:71], v[144:147], v[192:195], v[68:71]
	v_mfma_f32_16x16x32_bf16 v[64:67], v[8:11], v[200:203], v[64:67]
	v_mfma_f32_16x16x32_bf16 v[56:59], v[144:147], v[200:203], v[56:59]
	v_mfma_f32_16x16x32_bf16 v[48:51], v[8:11], v[212:215], v[48:51]
	v_mfma_f32_16x16x32_bf16 v[40:43], v[144:147], v[212:215], v[40:43]
	v_mfma_f32_16x16x32_bf16 v[4:7], v[8:11], v[220:223], v[4:7]
	v_mfma_f32_16x16x32_bf16 v[8:11], v[140:143], v[216:219], v[24:27]
	v_mfma_f32_16x16x32_bf16 v[8:11], v[144:147], v[220:223], v[8:11]
	v_mfma_f32_16x16x32_bf16 v[24:27], v[172:175], v[188:191], v[60:63]
	v_mfma_f32_16x16x32_bf16 v[60:63], v[176:179], v[192:195], v[24:27]
	v_mfma_f32_16x16x32_bf16 v[24:27], v[180:183], v[188:191], v[52:55]
	v_mfma_f32_16x16x32_bf16 v[52:55], v[184:187], v[192:195], v[24:27]
	v_mfma_f32_16x16x32_bf16 v[24:27], v[172:175], v[196:199], v[44:47]
	v_mfma_f32_16x16x32_bf16 v[44:47], v[176:179], v[200:203], v[24:27]
	v_mfma_f32_16x16x32_bf16 v[24:27], v[180:183], v[196:199], v[36:39]
	v_mfma_f32_16x16x32_bf16 v[36:39], v[184:187], v[200:203], v[24:27]
	v_mfma_f32_16x16x32_bf16 v[24:27], v[172:175], v[204:207], v[28:31]
	v_mfma_f32_16x16x32_bf16 v[20:23], v[180:183], v[204:207], v[20:23]
	v_mfma_f32_16x16x32_bf16 v[16:19], v[172:175], v[216:219], v[16:19]
	v_mfma_f32_16x16x32_bf16 v[12:15], v[180:183], v[216:219], v[12:15]
	v_mfma_f32_16x16x32_bf16 v[28:31], v[176:179], v[212:215], v[24:27]
	v_mfma_f32_16x16x32_bf16 v[20:23], v[184:187], v[212:215], v[20:23]
	v_mfma_f32_16x16x32_bf16 v[16:19], v[176:179], v[220:223], v[16:19]
	v_mfma_f32_16x16x32_bf16 v[12:15], v[184:187], v[220:223], v[12:15]
	s_barrier
	s_setprio 0
	s_add_i32 s53, 0, 0x18000
	s_add_i32 s54, 0, 0x1c000
	v_add_u32_e32 v144, s53, v168
	v_add_u32_e32 v171, s54, v168
	ds_read_b128 v[24:27], v144
	ds_read_b128 v[32:35], v144 offset:1024
	ds_read_b128 v[140:143], v144 offset:2048
	ds_read_b128 v[144:147], v144 offset:3072
	ds_read_b128 v[172:175], v171
	ds_read_b128 v[176:179], v171 offset:1024
	ds_read_b128 v[180:183], v171 offset:2048
	ds_read_b128 v[184:187], v171 offset:3072
	s_add_u32 s34, s38, 0x80000
	s_addc_u32 s35, s39, 0
	s_mov_b32 m0, s47
	ds_read_b128 v[188:191], v170 offset:32768
	ds_read_b128 v[192:195], v170 offset:33792
	ds_read_b128 v[196:199], v170 offset:34816
	ds_read_b128 v[200:203], v170 offset:35840
	ds_read_b128 v[204:207], v170 offset:36864
	ds_read_b128 v[212:215], v170 offset:37888
	ds_read_b128 v[216:219], v170 offset:38912
	ds_read_b128 v[220:223], v170 offset:39936
	global_load_lds_dwordx4 v152, s[34:35]
	s_mov_b32 m0, s48
	s_nop 0
	global_load_lds_dwordx4 v150, s[34:35]
	s_waitcnt vmcnt(8)
	s_waitcnt lgkmcnt(0)
	s_setprio 1
	s_barrier
	v_mfma_f32_16x16x32_bf16 v[136:139], v[24:27], v[188:191], v[136:139]
	v_mfma_f32_16x16x32_bf16 v[132:135], v[140:143], v[188:191], v[132:135]
	v_mfma_f32_16x16x32_bf16 v[128:131], v[24:27], v[196:199], v[128:131]
	v_mfma_f32_16x16x32_bf16 v[120:123], v[140:143], v[196:199], v[120:123]
	v_mfma_f32_16x16x32_bf16 v[112:115], v[24:27], v[204:207], v[112:115]
	v_mfma_f32_16x16x32_bf16 v[104:107], v[140:143], v[204:207], v[104:107]
	v_mfma_f32_16x16x32_bf16 v[96:99], v[24:27], v[216:219], v[96:99]
	v_mfma_f32_16x16x32_bf16 v[88:91], v[140:143], v[216:219], v[88:91]
	v_mfma_f32_16x16x32_bf16 v[136:139], v[32:35], v[192:195], v[136:139]
	v_mfma_f32_16x16x32_bf16 v[132:135], v[144:147], v[192:195], v[132:135]
	v_mfma_f32_16x16x32_bf16 v[128:131], v[32:35], v[200:203], v[128:131]
	v_mfma_f32_16x16x32_bf16 v[120:123], v[144:147], v[200:203], v[120:123]
	v_mfma_f32_16x16x32_bf16 v[112:115], v[32:35], v[212:215], v[112:115]
	v_mfma_f32_16x16x32_bf16 v[104:107], v[144:147], v[212:215], v[104:107]
	v_mfma_f32_16x16x32_bf16 v[96:99], v[32:35], v[220:223], v[96:99]
	v_mfma_f32_16x16x32_bf16 v[88:91], v[144:147], v[220:223], v[88:91]
	v_mfma_f32_16x16x32_bf16 v[124:127], v[172:175], v[188:191], v[124:127]
	v_mfma_f32_16x16x32_bf16 v[116:119], v[180:183], v[188:191], v[116:119]
	v_mfma_f32_16x16x32_bf16 v[108:111], v[172:175], v[196:199], v[108:111]
	v_mfma_f32_16x16x32_bf16 v[100:103], v[180:183], v[196:199], v[100:103]
	v_mfma_f32_16x16x32_bf16 v[92:95], v[172:175], v[204:207], v[92:95]
	v_mfma_f32_16x16x32_bf16 v[84:87], v[180:183], v[204:207], v[84:87]
	v_mfma_f32_16x16x32_bf16 v[80:83], v[172:175], v[216:219], v[80:83]
	v_mfma_f32_16x16x32_bf16 v[76:79], v[180:183], v[216:219], v[76:79]
	v_mfma_f32_16x16x32_bf16 v[124:127], v[176:179], v[192:195], v[124:127]
	v_mfma_f32_16x16x32_bf16 v[116:119], v[184:187], v[192:195], v[116:119]
	v_mfma_f32_16x16x32_bf16 v[108:111], v[176:179], v[200:203], v[108:111]
	v_mfma_f32_16x16x32_bf16 v[100:103], v[184:187], v[200:203], v[100:103]
	v_mfma_f32_16x16x32_bf16 v[92:95], v[176:179], v[212:215], v[92:95]
	v_mfma_f32_16x16x32_bf16 v[84:87], v[184:187], v[212:215], v[84:87]
	v_mfma_f32_16x16x32_bf16 v[80:83], v[176:179], v[220:223], v[80:83]
	v_mfma_f32_16x16x32_bf16 v[76:79], v[184:187], v[220:223], v[76:79]
	s_barrier
	s_setprio 0
	s_add_i32 s34, s53, s7
	s_mov_b32 m0, s34
	ds_read_b128 v[188:191], v170 offset:49152
	ds_read_b128 v[192:195], v170 offset:50176
	ds_read_b128 v[196:199], v170 offset:51200
	ds_read_b128 v[200:203], v170 offset:52224
	ds_read_b128 v[204:207], v170 offset:53248
	ds_read_b128 v[212:215], v170 offset:54272
	ds_read_b128 v[216:219], v170 offset:55296
	ds_read_b128 v[220:223], v170 offset:56320
	global_load_lds_dwordx4 v2, s[98:99]
	s_add_i32 m0, s34, 0x2000
	s_add_u32 s26, s26, 0x80080
	s_addc_u32 s27, s27, 0
	s_add_i32 s34, s54, s7
	global_load_lds_dwordx4 v148, s[98:99]
	s_mov_b32 m0, s34
	s_nop 0
	global_load_lds_dwordx4 v2, s[26:27]
	s_add_i32 m0, s34, 0x2000
	s_nop 0
	global_load_lds_dwordx4 v148, s[26:27]
	s_mov_b32 m0, s49
	s_nop 0
	global_load_lds_dwordx4 v152, s[100:101]
	s_mov_b32 m0, s50
	s_nop 0
	global_load_lds_dwordx4 v150, s[100:101]
	s_waitcnt vmcnt(8)
	s_waitcnt lgkmcnt(0)
	s_setprio 1
	s_barrier
	v_mfma_f32_16x16x32_bf16 v[72:75], v[24:27], v[188:191], v[72:75]
	v_mfma_f32_16x16x32_bf16 v[64:67], v[24:27], v[196:199], v[64:67]
	v_mfma_f32_16x16x32_bf16 v[48:51], v[24:27], v[204:207], v[48:51]
	v_mfma_f32_16x16x32_bf16 v[4:7], v[24:27], v[216:219], v[4:7]
	v_mfma_f32_16x16x32_bf16 v[72:75], v[32:35], v[192:195], v[72:75]
	v_mfma_f32_16x16x32_bf16 v[68:71], v[140:143], v[188:191], v[68:71]
	v_mfma_f32_16x16x32_bf16 v[64:67], v[32:35], v[200:203], v[64:67]
	v_mfma_f32_16x16x32_bf16 v[56:59], v[140:143], v[196:199], v[56:59]
	v_mfma_f32_16x16x32_bf16 v[48:51], v[32:35], v[212:215], v[48:51]
	v_mfma_f32_16x16x32_bf16 v[40:43], v[140:143], v[204:207], v[40:43]
	v_mfma_f32_16x16x32_bf16 v[32:35], v[32:35], v[220:223], v[4:7]
	v_mfma_f32_16x16x32_bf16 v[4:7], v[140:143], v[216:219], v[8:11]
	v_mfma_f32_16x16x32_bf16 v[68:71], v[144:147], v[192:195], v[68:71]
	v_mfma_f32_16x16x32_bf16 v[56:59], v[144:147], v[200:203], v[56:59]
	v_mfma_f32_16x16x32_bf16 v[40:43], v[144:147], v[212:215], v[40:43]
	v_mfma_f32_16x16x32_bf16 v[24:27], v[144:147], v[220:223], v[4:7]
	v_mfma_f32_16x16x32_bf16 v[4:7], v[172:175], v[188:191], v[60:63]
	v_mfma_f32_16x16x32_bf16 v[60:63], v[176:179], v[192:195], v[4:7]
	v_mfma_f32_16x16x32_bf16 v[4:7], v[180:183], v[188:191], v[52:55]
	v_mfma_f32_16x16x32_bf16 v[52:55], v[184:187], v[192:195], v[4:7]
	v_mfma_f32_16x16x32_bf16 v[4:7], v[172:175], v[196:199], v[44:47]
	v_mfma_f32_16x16x32_bf16 v[44:47], v[176:179], v[200:203], v[4:7]
	v_mfma_f32_16x16x32_bf16 v[4:7], v[180:183], v[196:199], v[36:39]
	v_mfma_f32_16x16x32_bf16 v[36:39], v[184:187], v[200:203], v[4:7]
	v_mfma_f32_16x16x32_bf16 v[4:7], v[172:175], v[204:207], v[28:31]
	v_mfma_f32_16x16x32_bf16 v[28:31], v[176:179], v[212:215], v[4:7]
	v_mfma_f32_16x16x32_bf16 v[4:7], v[180:183], v[204:207], v[20:23]
	v_mfma_f32_16x16x32_bf16 v[20:23], v[184:187], v[212:215], v[4:7]
	v_mfma_f32_16x16x32_bf16 v[4:7], v[172:175], v[216:219], v[16:19]
	v_mfma_f32_16x16x32_bf16 v[16:19], v[176:179], v[220:223], v[4:7]
	v_mfma_f32_16x16x32_bf16 v[4:7], v[180:183], v[216:219], v[12:15]
	v_mfma_f32_16x16x32_bf16 v[12:15], v[184:187], v[220:223], v[4:7]
	s_barrier
	s_setprio 0
	s_add_i32 s33, s33, 2
	s_add_u32 s22, s22, 0x1000
	s_addc_u32 s23, s23, 0
	s_add_u32 s15, s15, 0x100
	s_addc_u32 s17, s17, 0
	s_cmp_gt_u32 s33, 27
	s_cbranch_scc0 .LBB0_489
.Llast_489:
	s_add_u32 s26, s22, 0xfff80800
	s_addc_u32 s27, s23, -1
	s_add_i32 s34, 0, 0x10000
	s_cmp_eq_u32 s33, 28
	s_cselect_b32 s39, s3, s27
	s_cselect_b32 s38, s6, s26
	s_cselect_b32 s27, s8, s17
	s_cselect_b32 s26, s9, s15
	s_add_i32 s53, 0, 0x14000
	v_add_u32_e32 v144, s34, v168
	v_add_u32_e32 v160, s53, v168
	ds_read_b128 v[4:7], v144
	ds_read_b128 v[8:11], v144 offset:1024
	ds_read_b128 v[140:143], v144 offset:2048
	ds_read_b128 v[144:147], v144 offset:3072
	ds_read_b128 v[172:175], v160
	ds_read_b128 v[176:179], v160 offset:1024
	ds_read_b128 v[180:183], v160 offset:2048
	ds_read_b128 v[184:187], v160 offset:3072
	s_add_i32 m0, s13, 0xc000
	ds_read_b128 v[188:191], v170
	ds_read_b128 v[192:195], v170 offset:1024
	ds_read_b128 v[196:199], v170 offset:2048
	ds_read_b128 v[200:203], v170 offset:3072
	ds_read_b128 v[204:207], v170 offset:4096
	ds_read_b128 v[212:215], v170 offset:5120
	ds_read_b128 v[216:219], v170 offset:6144
	ds_read_b128 v[220:223], v170 offset:7168
	global_load_lds_dwordx4 v156, s[22:23]
	s_add_i32 m0, s13, 0xe000
	s_nop 0
	global_load_lds_dwordx4 v158, s[22:23]
	s_waitcnt vmcnt(8)
	s_waitcnt lgkmcnt(0)
	s_setprio 1
	s_barrier
	v_mfma_f32_16x16x32_bf16 v[136:139], v[4:7], v[188:191], v[136:139]
	v_mfma_f32_16x16x32_bf16 v[132:135], v[140:143], v[188:191], v[132:135]
	v_mfma_f32_16x16x32_bf16 v[128:131], v[4:7], v[196:199], v[128:131]
	v_mfma_f32_16x16x32_bf16 v[120:123], v[140:143], v[196:199], v[120:123]
	v_mfma_f32_16x16x32_bf16 v[112:115], v[4:7], v[204:207], v[112:115]
	v_mfma_f32_16x16x32_bf16 v[104:107], v[140:143], v[204:207], v[104:107]
	v_mfma_f32_16x16x32_bf16 v[96:99], v[4:7], v[216:219], v[96:99]
	v_mfma_f32_16x16x32_bf16 v[88:91], v[140:143], v[216:219], v[88:91]
	v_mfma_f32_16x16x32_bf16 v[136:139], v[8:11], v[192:195], v[136:139]
	v_mfma_f32_16x16x32_bf16 v[132:135], v[144:147], v[192:195], v[132:135]
	v_mfma_f32_16x16x32_bf16 v[128:131], v[8:11], v[200:203], v[128:131]
	v_mfma_f32_16x16x32_bf16 v[120:123], v[144:147], v[200:203], v[120:123]
	v_mfma_f32_16x16x32_bf16 v[112:115], v[8:11], v[212:215], v[112:115]
	v_mfma_f32_16x16x32_bf16 v[104:107], v[144:147], v[212:215], v[104:107]
	v_mfma_f32_16x16x32_bf16 v[96:99], v[8:11], v[220:223], v[96:99]
	v_mfma_f32_16x16x32_bf16 v[88:91], v[144:147], v[220:223], v[88:91]
	v_mfma_f32_16x16x32_bf16 v[124:127], v[172:175], v[188:191], v[124:127]
	v_mfma_f32_16x16x32_bf16 v[116:119], v[180:183], v[188:191], v[116:119]
	v_mfma_f32_16x16x32_bf16 v[108:111], v[172:175], v[196:199], v[108:111]
	v_mfma_f32_16x16x32_bf16 v[100:103], v[180:183], v[196:199], v[100:103]
	v_mfma_f32_16x16x32_bf16 v[92:95], v[172:175], v[204:207], v[92:95]
	v_mfma_f32_16x16x32_bf16 v[84:87], v[180:183], v[204:207], v[84:87]
	v_mfma_f32_16x16x32_bf16 v[80:83], v[172:175], v[216:219], v[80:83]
	v_mfma_f32_16x16x32_bf16 v[76:79], v[180:183], v[216:219], v[76:79]
	v_mfma_f32_16x16x32_bf16 v[124:127], v[176:179], v[192:195], v[124:127]
	v_mfma_f32_16x16x32_bf16 v[116:119], v[184:187], v[192:195], v[116:119]
	v_mfma_f32_16x16x32_bf16 v[108:111], v[176:179], v[200:203], v[108:111]
	v_mfma_f32_16x16x32_bf16 v[100:103], v[184:187], v[200:203], v[100:103]
	v_mfma_f32_16x16x32_bf16 v[92:95], v[176:179], v[212:215], v[92:95]
	v_mfma_f32_16x16x32_bf16 v[84:87], v[184:187], v[212:215], v[84:87]
	v_mfma_f32_16x16x32_bf16 v[80:83], v[176:179], v[220:223], v[80:83]
	v_mfma_f32_16x16x32_bf16 v[76:79], v[184:187], v[220:223], v[76:79]
	s_barrier
	s_setprio 0
	s_add_i32 s34, s34, s7
	s_add_u32 s98, s26, 0x80
	s_addc_u32 s99, s27, 0
	s_add_u32 s100, s38, 0x800
	s_addc_u32 s101, s39, 0
	s_mov_b32 m0, s34
	ds_read_b128 v[188:191], v170 offset:16384
	ds_read_b128 v[192:195], v170 offset:17408
	ds_read_b128 v[196:199], v170 offset:18432
	ds_read_b128 v[200:203], v170 offset:19456
	ds_read_b128 v[204:207], v170 offset:20480
	ds_read_b128 v[212:215], v170 offset:21504
	ds_read_b128 v[216:219], v170 offset:22528
	ds_read_b128 v[220:223], v170 offset:23552
	global_load_lds_dwordx4 v2, s[26:27]
	s_add_i32 m0, s34, 0x2000
	s_add_u32 s34, s26, 0x80000
	s_addc_u32 s35, s27, 0
	s_add_i32 s53, s53, s7
	global_load_lds_dwordx4 v148, s[26:27]
	s_mov_b32 m0, s53
	s_nop 0
	global_load_lds_dwordx4 v2, s[34:35]
	s_add_i32 m0, s53, 0x2000
	s_nop 0
	global_load_lds_dwordx4 v148, s[34:35]
	s_mov_b32 m0, s13
	s_nop 0
	global_load_lds_dwordx4 v152, s[38:39]
	s_mov_b32 m0, s46
	s_nop 0
	global_load_lds_dwordx4 v150, s[38:39]
	s_waitcnt vmcnt(8)
	s_waitcnt lgkmcnt(0)
	s_setprio 1
	s_barrier
	v_mfma_f32_16x16x32_bf16 v[72:75], v[4:7], v[188:191], v[72:75]
	v_mfma_f32_16x16x32_bf16 v[68:71], v[140:143], v[188:191], v[68:71]
	v_mfma_f32_16x16x32_bf16 v[64:67], v[4:7], v[196:199], v[64:67]
	v_mfma_f32_16x16x32_bf16 v[56:59], v[140:143], v[196:199], v[56:59]
	v_mfma_f32_16x16x32_bf16 v[48:51], v[4:7], v[204:207], v[48:51]
	v_mfma_f32_16x16x32_bf16 v[40:43], v[140:143], v[204:207], v[40:43]
	v_mfma_f32_16x16x32_bf16 v[4:7], v[4:7], v[216:219], v[32:35]
	v_mfma_f32_16x16x32_bf16 v[72:75], v[8:11], v[192:195], v[72:75]
	v_mfma_f32_16x16x32_bf16 v[68:71], v[144:147], v[192:195], v[68:71]
	v_mfma_f32_16x16x32_bf16 v[64:67], v[8:11], v[200:203], v[64:67]
	v_mfma_f32_16x16x32_bf16 v[56:59], v[144:147], v[200:203], v[56:59]
	v_mfma_f32_16x16x32_bf16 v[48:51], v[8:11], v[212:215], v[48:51]
	v_mfma_f32_16x16x32_bf16 v[40:43], v[144:147], v[212:215], v[40:43]
	v_mfma_f32_16x16x32_bf16 v[4:7], v[8:11], v[220:223], v[4:7]
	v_mfma_f32_16x16x32_bf16 v[8:11], v[140:143], v[216:219], v[24:27]
	v_mfma_f32_16x16x32_bf16 v[8:11], v[144:147], v[220:223], v[8:11]
	v_mfma_f32_16x16x32_bf16 v[24:27], v[172:175], v[188:191], v[60:63]
	v_mfma_f32_16x16x32_bf16 v[60:63], v[176:179], v[192:195], v[24:27]
	v_mfma_f32_16x16x32_bf16 v[24:27], v[180:183], v[188:191], v[52:55]
	v_mfma_f32_16x16x32_bf16 v[52:55], v[184:187], v[192:195], v[24:27]
	v_mfma_f32_16x16x32_bf16 v[24:27], v[172:175], v[196:199], v[44:47]
	v_mfma_f32_16x16x32_bf16 v[44:47], v[176:179], v[200:203], v[24:27]
	v_mfma_f32_16x16x32_bf16 v[24:27], v[180:183], v[196:199], v[36:39]
	v_mfma_f32_16x16x32_bf16 v[36:39], v[184:187], v[200:203], v[24:27]
	v_mfma_f32_16x16x32_bf16 v[24:27], v[172:175], v[204:207], v[28:31]
	v_mfma_f32_16x16x32_bf16 v[20:23], v[180:183], v[204:207], v[20:23]
	v_mfma_f32_16x16x32_bf16 v[16:19], v[172:175], v[216:219], v[16:19]
	v_mfma_f32_16x16x32_bf16 v[12:15], v[180:183], v[216:219], v[12:15]
	v_mfma_f32_16x16x32_bf16 v[28:31], v[176:179], v[212:215], v[24:27]
	v_mfma_f32_16x16x32_bf16 v[20:23], v[184:187], v[212:215], v[20:23]
	v_mfma_f32_16x16x32_bf16 v[16:19], v[176:179], v[220:223], v[16:19]
	v_mfma_f32_16x16x32_bf16 v[12:15], v[184:187], v[220:223], v[12:15]
	s_barrier
	s_setprio 0
	s_add_i32 s53, 0, 0x18000
	s_add_i32 s54, 0, 0x1c000
	v_add_u32_e32 v144, s53, v168
	v_add_u32_e32 v171, s54, v168
	ds_read_b128 v[24:27], v144
	ds_read_b128 v[32:35], v144 offset:1024
	ds_read_b128 v[140:143], v144 offset:2048
	ds_read_b128 v[144:147], v144 offset:3072
	ds_read_b128 v[172:175], v171
	ds_read_b128 v[176:179], v171 offset:1024
	ds_read_b128 v[180:183], v171 offset:2048
	ds_read_b128 v[184:187], v171 offset:3072
	s_add_u32 s34, s38, 0x80000
	s_addc_u32 s35, s39, 0
	s_mov_b32 m0, s47
	ds_read_b128 v[188:191], v170 offset:32768
	ds_read_b128 v[192:195], v170 offset:33792
	ds_read_b128 v[196:199], v170 offset:34816
	ds_read_b128 v[200:203], v170 offset:35840
	ds_read_b128 v[204:207], v170 offset:36864
	ds_read_b128 v[212:215], v170 offset:37888
	ds_read_b128 v[216:219], v170 offset:38912
	ds_read_b128 v[220:223], v170 offset:39936
	global_load_lds_dwordx4 v152, s[34:35]
	s_mov_b32 m0, s48
	s_nop 0
	global_load_lds_dwordx4 v150, s[34:35]
	s_waitcnt vmcnt(8)
	s_waitcnt lgkmcnt(0)
	s_setprio 1
	s_barrier
	v_mfma_f32_16x16x32_bf16 v[136:139], v[24:27], v[188:191], v[136:139]
	v_mfma_f32_16x16x32_bf16 v[132:135], v[140:143], v[188:191], v[132:135]
	v_mfma_f32_16x16x32_bf16 v[128:131], v[24:27], v[196:199], v[128:131]
	v_mfma_f32_16x16x32_bf16 v[120:123], v[140:143], v[196:199], v[120:123]
	v_mfma_f32_16x16x32_bf16 v[112:115], v[24:27], v[204:207], v[112:115]
	v_mfma_f32_16x16x32_bf16 v[104:107], v[140:143], v[204:207], v[104:107]
	v_mfma_f32_16x16x32_bf16 v[96:99], v[24:27], v[216:219], v[96:99]
	v_mfma_f32_16x16x32_bf16 v[88:91], v[140:143], v[216:219], v[88:91]
	v_mfma_f32_16x16x32_bf16 v[136:139], v[32:35], v[192:195], v[136:139]
	v_mfma_f32_16x16x32_bf16 v[132:135], v[144:147], v[192:195], v[132:135]
	v_mfma_f32_16x16x32_bf16 v[128:131], v[32:35], v[200:203], v[128:131]
	v_mfma_f32_16x16x32_bf16 v[120:123], v[144:147], v[200:203], v[120:123]
	v_mfma_f32_16x16x32_bf16 v[112:115], v[32:35], v[212:215], v[112:115]
	v_mfma_f32_16x16x32_bf16 v[104:107], v[144:147], v[212:215], v[104:107]
	v_mfma_f32_16x16x32_bf16 v[96:99], v[32:35], v[220:223], v[96:99]
	v_mfma_f32_16x16x32_bf16 v[88:91], v[144:147], v[220:223], v[88:91]
	v_mfma_f32_16x16x32_bf16 v[124:127], v[172:175], v[188:191], v[124:127]
	v_mfma_f32_16x16x32_bf16 v[116:119], v[180:183], v[188:191], v[116:119]
	v_mfma_f32_16x16x32_bf16 v[108:111], v[172:175], v[196:199], v[108:111]
	v_mfma_f32_16x16x32_bf16 v[100:103], v[180:183], v[196:199], v[100:103]
	v_mfma_f32_16x16x32_bf16 v[92:95], v[172:175], v[204:207], v[92:95]
	v_mfma_f32_16x16x32_bf16 v[84:87], v[180:183], v[204:207], v[84:87]
	v_mfma_f32_16x16x32_bf16 v[80:83], v[172:175], v[216:219], v[80:83]
	v_mfma_f32_16x16x32_bf16 v[76:79], v[180:183], v[216:219], v[76:79]
	v_mfma_f32_16x16x32_bf16 v[124:127], v[176:179], v[192:195], v[124:127]
	v_mfma_f32_16x16x32_bf16 v[116:119], v[184:187], v[192:195], v[116:119]
	v_mfma_f32_16x16x32_bf16 v[108:111], v[176:179], v[200:203], v[108:111]
	v_mfma_f32_16x16x32_bf16 v[100:103], v[184:187], v[200:203], v[100:103]
	v_mfma_f32_16x16x32_bf16 v[92:95], v[176:179], v[212:215], v[92:95]
	v_mfma_f32_16x16x32_bf16 v[84:87], v[184:187], v[212:215], v[84:87]
	v_mfma_f32_16x16x32_bf16 v[80:83], v[176:179], v[220:223], v[80:83]
	v_mfma_f32_16x16x32_bf16 v[76:79], v[184:187], v[220:223], v[76:79]
	s_barrier
	s_setprio 0
	s_add_i32 s34, s53, s7
	s_mov_b32 m0, s34
	ds_read_b128 v[188:191], v170 offset:49152
	ds_read_b128 v[192:195], v170 offset:50176
	ds_read_b128 v[196:199], v170 offset:51200
	ds_read_b128 v[200:203], v170 offset:52224
	ds_read_b128 v[204:207], v170 offset:53248
	ds_read_b128 v[212:215], v170 offset:54272
	ds_read_b128 v[216:219], v170 offset:55296
	ds_read_b128 v[220:223], v170 offset:56320
	global_load_lds_dwordx4 v2, s[98:99]
	s_add_i32 m0, s34, 0x2000
	s_add_u32 s26, s26, 0x80080
	s_addc_u32 s27, s27, 0
	s_add_i32 s34, s54, s7
	global_load_lds_dwordx4 v148, s[98:99]
	s_mov_b32 m0, s34
	s_nop 0
	global_load_lds_dwordx4 v2, s[26:27]
	s_add_i32 m0, s34, 0x2000
	s_nop 0
	global_load_lds_dwordx4 v148, s[26:27]
	s_mov_b32 m0, s49
	s_nop 0
	global_load_lds_dwordx4 v152, s[100:101]
	s_mov_b32 m0, s50
	s_nop 0
	global_load_lds_dwordx4 v150, s[100:101]
	s_waitcnt vmcnt(8)
	s_waitcnt lgkmcnt(0)
	s_setprio 1
	s_barrier
	v_mfma_f32_16x16x32_bf16 v[72:75], v[24:27], v[188:191], v[72:75]
	v_mfma_f32_16x16x32_bf16 v[64:67], v[24:27], v[196:199], v[64:67]
	v_mfma_f32_16x16x32_bf16 v[48:51], v[24:27], v[204:207], v[48:51]
	v_mfma_f32_16x16x32_bf16 v[4:7], v[24:27], v[216:219], v[4:7]
	v_mfma_f32_16x16x32_bf16 v[72:75], v[32:35], v[192:195], v[72:75]
	v_mfma_f32_16x16x32_bf16 v[68:71], v[140:143], v[188:191], v[68:71]
	v_mfma_f32_16x16x32_bf16 v[64:67], v[32:35], v[200:203], v[64:67]
	v_mfma_f32_16x16x32_bf16 v[56:59], v[140:143], v[196:199], v[56:59]
	v_mfma_f32_16x16x32_bf16 v[48:51], v[32:35], v[212:215], v[48:51]
	v_mfma_f32_16x16x32_bf16 v[40:43], v[140:143], v[204:207], v[40:43]
	v_mfma_f32_16x16x32_bf16 v[32:35], v[32:35], v[220:223], v[4:7]
	v_mfma_f32_16x16x32_bf16 v[4:7], v[140:143], v[216:219], v[8:11]
	v_mfma_f32_16x16x32_bf16 v[68:71], v[144:147], v[192:195], v[68:71]
	v_mfma_f32_16x16x32_bf16 v[56:59], v[144:147], v[200:203], v[56:59]
	v_mfma_f32_16x16x32_bf16 v[40:43], v[144:147], v[212:215], v[40:43]
	v_mfma_f32_16x16x32_bf16 v[24:27], v[144:147], v[220:223], v[4:7]
	v_mfma_f32_16x16x32_bf16 v[4:7], v[172:175], v[188:191], v[60:63]
	v_mfma_f32_16x16x32_bf16 v[60:63], v[176:179], v[192:195], v[4:7]
	v_mfma_f32_16x16x32_bf16 v[4:7], v[180:183], v[188:191], v[52:55]
	v_mfma_f32_16x16x32_bf16 v[52:55], v[184:187], v[192:195], v[4:7]
	v_mfma_f32_16x16x32_bf16 v[4:7], v[172:175], v[196:199], v[44:47]
	v_mfma_f32_16x16x32_bf16 v[44:47], v[176:179], v[200:203], v[4:7]
	v_mfma_f32_16x16x32_bf16 v[4:7], v[180:183], v[196:199], v[36:39]
	v_mfma_f32_16x16x32_bf16 v[36:39], v[184:187], v[200:203], v[4:7]
	v_mfma_f32_16x16x32_bf16 v[4:7], v[172:175], v[204:207], v[28:31]
	v_mfma_f32_16x16x32_bf16 v[28:31], v[176:179], v[212:215], v[4:7]
	v_mfma_f32_16x16x32_bf16 v[4:7], v[180:183], v[204:207], v[20:23]
	v_mfma_f32_16x16x32_bf16 v[20:23], v[184:187], v[212:215], v[4:7]
	v_mfma_f32_16x16x32_bf16 v[4:7], v[172:175], v[216:219], v[16:19]
	v_mfma_f32_16x16x32_bf16 v[16:19], v[176:179], v[220:223], v[4:7]
	v_mfma_f32_16x16x32_bf16 v[4:7], v[180:183], v[216:219], v[12:15]
	v_mfma_f32_16x16x32_bf16 v[12:15], v[184:187], v[220:223], v[4:7]
	s_setprio 0
	s_add_i32 s33, s33, 2
	s_add_u32 s22, s22, 0x1000
	s_addc_u32 s23, s23, 0
	s_add_u32 s15, s15, 0x100
	s_addc_u32 s17, s17, 0

.LBB0_831:
	s_lshl_b32 s98, s100, 1
	s_add_u32 s2, s2, s100
	s_addc_u32 s3, s3, 0
	s_add_u32 s7, s22, 0x100
	s_addc_u32 s8, s23, 0
	s_mov_b32 s9, 0
	s_add_i32 s28, s9, 2
	s_add_u32 s22, s2, s100
	s_addc_u32 s23, s3, 0
	s_add_i32 s29, 0, 0x10000
	s_cmp_eq_u32 s52, s9
	s_cselect_b32 s23, s1, s23
	s_cselect_b32 s22, s0, s22
	v_add_u32_e32 v2, s29, v147
	s_cselect_b32 s35, s21, s8
	s_cselect_b32 s34, s20, s7
	s_add_i32 s9, 0, 0x14000
	ds_read_b128 v[152:155], v2
	ds_read_b128 v[156:159], v2 offset:1024
	ds_read_b128 v[160:163], v2 offset:2048
	ds_read_b128 v[168:171], v2 offset:3072
	v_add_u32_e32 v2, s9, v147
	ds_read_b128 v[172:175], v2
	ds_read_b128 v[176:179], v2 offset:1024
	ds_read_b128 v[180:183], v2 offset:2048
	ds_read_b128 v[184:187], v2 offset:3072
	s_add_i32 m0, s47, 0xc000
	ds_read_b128 v[188:191], v150
	ds_read_b128 v[192:195], v150 offset:1024
	ds_read_b128 v[196:199], v150 offset:2048
	ds_read_b128 v[200:203], v150 offset:3072
	ds_read_b128 v[204:207], v150 offset:4096
	ds_read_b128 v[210:213], v150 offset:5120
	ds_read_b128 v[214:217], v150 offset:6144
	ds_read_b128 v[218:221], v150 offset:7168
	global_load_lds_dwordx4 v140, s[2:3]
	s_add_i32 m0, s47, 0xe000
	s_nop 0
	global_load_lds_dwordx4 v142, s[2:3]
	s_waitcnt vmcnt(8)
	s_waitcnt lgkmcnt(0)
	s_setprio 1
	s_barrier
	v_mfma_f32_16x16x32_bf16 v[128:131], v[152:155], v[188:191], 0
	v_mfma_f32_16x16x32_bf16 v[124:127], v[160:163], v[188:191], 0
	v_mfma_f32_16x16x32_bf16 v[112:115], v[152:155], v[196:199], 0
	v_mfma_f32_16x16x32_bf16 v[108:111], v[160:163], v[196:199], 0
	v_mfma_f32_16x16x32_bf16 v[96:99], v[152:155], v[204:207], 0
	v_mfma_f32_16x16x32_bf16 v[92:95], v[160:163], v[204:207], 0
	v_mfma_f32_16x16x32_bf16 v[80:83], v[152:155], v[214:217], 0
	v_mfma_f32_16x16x32_bf16 v[76:79], v[160:163], v[214:217], 0
	v_mfma_f32_16x16x32_bf16 v[128:131], v[156:159], v[192:195], v[128:131]
	v_mfma_f32_16x16x32_bf16 v[124:127], v[168:171], v[192:195], v[124:127]
	v_mfma_f32_16x16x32_bf16 v[112:115], v[156:159], v[200:203], v[112:115]
	v_mfma_f32_16x16x32_bf16 v[108:111], v[168:171], v[200:203], v[108:111]
	v_mfma_f32_16x16x32_bf16 v[96:99], v[156:159], v[210:213], v[96:99]
	v_mfma_f32_16x16x32_bf16 v[92:95], v[168:171], v[210:213], v[92:95]
	v_mfma_f32_16x16x32_bf16 v[80:83], v[156:159], v[218:221], v[80:83]
	v_mfma_f32_16x16x32_bf16 v[76:79], v[168:171], v[218:221], v[76:79]
	v_mfma_f32_16x16x32_bf16 v[120:123], v[172:175], v[188:191], 0
	v_mfma_f32_16x16x32_bf16 v[116:119], v[180:183], v[188:191], 0
	v_mfma_f32_16x16x32_bf16 v[104:107], v[172:175], v[196:199], 0
	v_mfma_f32_16x16x32_bf16 v[100:103], v[180:183], v[196:199], 0
	v_mfma_f32_16x16x32_bf16 v[88:91], v[172:175], v[204:207], 0
	v_mfma_f32_16x16x32_bf16 v[84:87], v[180:183], v[204:207], 0
	v_mfma_f32_16x16x32_bf16 v[72:75], v[172:175], v[214:217], 0
	v_mfma_f32_16x16x32_bf16 v[68:71], v[180:183], v[214:217], 0
	v_mfma_f32_16x16x32_bf16 v[120:123], v[176:179], v[192:195], v[120:123]
	v_mfma_f32_16x16x32_bf16 v[116:119], v[184:187], v[192:195], v[116:119]
	v_mfma_f32_16x16x32_bf16 v[104:107], v[176:179], v[200:203], v[104:107]
	v_mfma_f32_16x16x32_bf16 v[100:103], v[184:187], v[200:203], v[100:103]
	v_mfma_f32_16x16x32_bf16 v[88:91], v[176:179], v[210:213], v[88:91]
	v_mfma_f32_16x16x32_bf16 v[84:87], v[184:187], v[210:213], v[84:87]
	v_mfma_f32_16x16x32_bf16 v[72:75], v[176:179], v[218:221], v[72:75]
	v_mfma_f32_16x16x32_bf16 v[68:71], v[184:187], v[218:221], v[68:71]
	s_barrier
	s_setprio 0
	s_add_i32 s29, s29, s26
	s_mov_b32 m0, s29
	ds_read_b128 v[188:191], v150 offset:16384
	ds_read_b128 v[192:195], v150 offset:17408
	ds_read_b128 v[196:199], v150 offset:18432
	ds_read_b128 v[200:203], v150 offset:19456
	ds_read_b128 v[204:207], v150 offset:20480
	ds_read_b128 v[210:213], v150 offset:21504
	ds_read_b128 v[214:217], v150 offset:22528
	ds_read_b128 v[218:221], v150 offset:23552
	global_load_lds_dwordx4 v136, s[34:35]
	s_add_i32 m0, s29, 0x2000
	s_add_i32 s9, s9, s26
	global_load_lds_dwordx4 v132, s[34:35]
	s_add_u32 s34, s34, s16
	s_addc_u32 s35, s35, 0
	s_mov_b32 m0, s9
	s_nop 0
	global_load_lds_dwordx4 v136, s[34:35]
	s_add_i32 m0, s9, 0x2000
	s_nop 0
	global_load_lds_dwordx4 v132, s[34:35]
	s_mov_b32 m0, s47
	s_nop 0
	global_load_lds_dwordx4 v138, s[22:23]
	s_mov_b32 m0, s48
	s_nop 0
	global_load_lds_dwordx4 v134, s[22:23]
	s_waitcnt vmcnt(8)
	s_waitcnt lgkmcnt(0)
	s_setprio 1
	s_barrier
	v_mfma_f32_16x16x32_bf16 v[64:67], v[152:155], v[188:191], 0
	v_mfma_f32_16x16x32_bf16 v[60:63], v[160:163], v[188:191], 0
	v_mfma_f32_16x16x32_bf16 v[48:51], v[152:155], v[196:199], 0
	v_mfma_f32_16x16x32_bf16 v[44:47], v[160:163], v[196:199], 0
	v_mfma_f32_16x16x32_bf16 v[32:35], v[152:155], v[204:207], 0
	v_mfma_f32_16x16x32_bf16 v[28:31], v[160:163], v[204:207], 0
	v_mfma_f32_16x16x32_bf16 v[16:19], v[152:155], v[214:217], 0
	v_mfma_f32_16x16x32_bf16 v[12:15], v[160:163], v[214:217], 0
	v_mfma_f32_16x16x32_bf16 v[64:67], v[156:159], v[192:195], v[64:67]
	v_mfma_f32_16x16x32_bf16 v[60:63], v[168:171], v[192:195], v[60:63]
	v_mfma_f32_16x16x32_bf16 v[48:51], v[156:159], v[200:203], v[48:51]
	v_mfma_f32_16x16x32_bf16 v[44:47], v[168:171], v[200:203], v[44:47]
	v_mfma_f32_16x16x32_bf16 v[32:35], v[156:159], v[210:213], v[32:35]
	v_mfma_f32_16x16x32_bf16 v[28:31], v[168:171], v[210:213], v[28:31]
	v_mfma_f32_16x16x32_bf16 v[16:19], v[156:159], v[218:221], v[16:19]
	v_mfma_f32_16x16x32_bf16 v[12:15], v[168:171], v[218:221], v[12:15]
	v_mfma_f32_16x16x32_bf16 v[56:59], v[172:175], v[188:191], 0
	v_mfma_f32_16x16x32_bf16 v[52:55], v[180:183], v[188:191], 0
	v_mfma_f32_16x16x32_bf16 v[40:43], v[172:175], v[196:199], 0
	v_mfma_f32_16x16x32_bf16 v[36:39], v[180:183], v[196:199], 0
	v_mfma_f32_16x16x32_bf16 v[24:27], v[172:175], v[204:207], 0
	v_mfma_f32_16x16x32_bf16 v[20:23], v[180:183], v[204:207], 0
	v_mfma_f32_16x16x32_bf16 v[8:11], v[172:175], v[214:217], 0
	v_mfma_f32_16x16x32_bf16 v[4:7], v[180:183], v[214:217], 0
	v_mfma_f32_16x16x32_bf16 v[56:59], v[176:179], v[192:195], v[56:59]
	v_mfma_f32_16x16x32_bf16 v[52:55], v[184:187], v[192:195], v[52:55]
	v_mfma_f32_16x16x32_bf16 v[40:43], v[176:179], v[200:203], v[40:43]
	v_mfma_f32_16x16x32_bf16 v[36:39], v[184:187], v[200:203], v[36:39]
	v_mfma_f32_16x16x32_bf16 v[24:27], v[176:179], v[210:213], v[24:27]
	v_mfma_f32_16x16x32_bf16 v[20:23], v[184:187], v[210:213], v[20:23]
	v_mfma_f32_16x16x32_bf16 v[8:11], v[176:179], v[218:221], v[8:11]
	v_mfma_f32_16x16x32_bf16 v[4:7], v[184:187], v[218:221], v[4:7]
	s_barrier
	s_setprio 0
	s_add_i32 s9, 0, 0x18000
	v_add_u32_e32 v2, s9, v147
	s_add_i32 s29, 0, 0x1c000
	ds_read_b128 v[152:155], v2
	ds_read_b128 v[156:159], v2 offset:1024
	ds_read_b128 v[160:163], v2 offset:2048
	ds_read_b128 v[168:171], v2 offset:3072
	v_add_u32_e32 v2, s29, v147
	ds_read_b128 v[172:175], v2
	ds_read_b128 v[176:179], v2 offset:1024
	ds_read_b128 v[180:183], v2 offset:2048
	ds_read_b128 v[184:187], v2 offset:3072
	s_add_u32 s22, s22, s16
	s_addc_u32 s23, s23, 0
	s_mov_b32 m0, s49
	ds_read_b128 v[188:191], v150 offset:32768
	ds_read_b128 v[192:195], v150 offset:33792
	ds_read_b128 v[196:199], v150 offset:34816
	ds_read_b128 v[200:203], v150 offset:35840
	ds_read_b128 v[204:207], v150 offset:36864
	ds_read_b128 v[210:213], v150 offset:37888
	ds_read_b128 v[214:217], v150 offset:38912
	ds_read_b128 v[218:221], v150 offset:39936
	global_load_lds_dwordx4 v138, s[22:23]
	s_mov_b32 m0, s50
	s_nop 0
	global_load_lds_dwordx4 v134, s[22:23]
	s_waitcnt vmcnt(8)
	s_waitcnt lgkmcnt(0)
	s_setprio 1
	s_barrier
	v_mfma_f32_16x16x32_bf16 v[128:131], v[152:155], v[188:191], v[128:131]
	v_mfma_f32_16x16x32_bf16 v[124:127], v[160:163], v[188:191], v[124:127]
	v_mfma_f32_16x16x32_bf16 v[112:115], v[152:155], v[196:199], v[112:115]
	v_mfma_f32_16x16x32_bf16 v[108:111], v[160:163], v[196:199], v[108:111]
	v_mfma_f32_16x16x32_bf16 v[96:99], v[152:155], v[204:207], v[96:99]
	v_mfma_f32_16x16x32_bf16 v[92:95], v[160:163], v[204:207], v[92:95]
	v_mfma_f32_16x16x32_bf16 v[80:83], v[152:155], v[214:217], v[80:83]
	v_mfma_f32_16x16x32_bf16 v[76:79], v[160:163], v[214:217], v[76:79]
	v_mfma_f32_16x16x32_bf16 v[128:131], v[156:159], v[192:195], v[128:131]
	v_mfma_f32_16x16x32_bf16 v[124:127], v[168:171], v[192:195], v[124:127]
	v_mfma_f32_16x16x32_bf16 v[112:115], v[156:159], v[200:203], v[112:115]
	v_mfma_f32_16x16x32_bf16 v[108:111], v[168:171], v[200:203], v[108:111]
	v_mfma_f32_16x16x32_bf16 v[96:99], v[156:159], v[210:213], v[96:99]
	v_mfma_f32_16x16x32_bf16 v[92:95], v[168:171], v[210:213], v[92:95]
	v_mfma_f32_16x16x32_bf16 v[80:83], v[156:159], v[218:221], v[80:83]
	v_mfma_f32_16x16x32_bf16 v[76:79], v[168:171], v[218:221], v[76:79]
	v_mfma_f32_16x16x32_bf16 v[120:123], v[172:175], v[188:191], v[120:123]
	v_mfma_f32_16x16x32_bf16 v[116:119], v[180:183], v[188:191], v[116:119]
	v_mfma_f32_16x16x32_bf16 v[104:107], v[172:175], v[196:199], v[104:107]
	v_mfma_f32_16x16x32_bf16 v[100:103], v[180:183], v[196:199], v[100:103]
	v_mfma_f32_16x16x32_bf16 v[88:91], v[172:175], v[204:207], v[88:91]
	v_mfma_f32_16x16x32_bf16 v[84:87], v[180:183], v[204:207], v[84:87]
	v_mfma_f32_16x16x32_bf16 v[72:75], v[172:175], v[214:217], v[72:75]
	v_mfma_f32_16x16x32_bf16 v[68:71], v[180:183], v[214:217], v[68:71]
	v_mfma_f32_16x16x32_bf16 v[120:123], v[176:179], v[192:195], v[120:123]
	v_mfma_f32_16x16x32_bf16 v[116:119], v[184:187], v[192:195], v[116:119]
	v_mfma_f32_16x16x32_bf16 v[104:107], v[176:179], v[200:203], v[104:107]
	v_mfma_f32_16x16x32_bf16 v[100:103], v[184:187], v[200:203], v[100:103]
	v_mfma_f32_16x16x32_bf16 v[88:91], v[176:179], v[210:213], v[88:91]
	v_mfma_f32_16x16x32_bf16 v[84:87], v[184:187], v[210:213], v[84:87]
	v_mfma_f32_16x16x32_bf16 v[72:75], v[176:179], v[218:221], v[72:75]
	v_mfma_f32_16x16x32_bf16 v[68:71], v[184:187], v[218:221], v[68:71]
	s_barrier
	s_setprio 0
	s_add_i32 s9, s9, s26
	s_mov_b32 m0, s9
	ds_read_b128 v[188:191], v150 offset:49152
	ds_read_b128 v[192:195], v150 offset:50176
	ds_read_b128 v[196:199], v150 offset:51200
	ds_read_b128 v[200:203], v150 offset:52224
	ds_read_b128 v[204:207], v150 offset:53248
	ds_read_b128 v[210:213], v150 offset:54272
	ds_read_b128 v[214:217], v150 offset:55296
	ds_read_b128 v[218:221], v150 offset:56320
	s_sub_u32 s34, s34, s16
	s_subb_u32 s35, s35, 0
	s_add_u32 s34, s34, 0x80
	s_addc_u32 s35, s35, 0
	global_load_lds_dwordx4 v136, s[34:35]
	s_add_i32 m0, s9, 0x2000
	s_add_i32 s9, s29, s26
	global_load_lds_dwordx4 v132, s[34:35]
	s_mov_b32 m0, s9
	s_nop 0
	s_add_u32 s34, s34, s16
	s_addc_u32 s35, s35, 0
	global_load_lds_dwordx4 v136, s[34:35]
	s_add_i32 m0, s9, 0x2000
	s_nop 0
	global_load_lds_dwordx4 v132, s[34:35]
	s_mov_b32 m0, s53
	s_nop 0
	s_sub_u32 s22, s22, s16
	s_subb_u32 s23, s23, 0
	s_add_u32 s22, s22, s100
	s_addc_u32 s23, s23, 0
	global_load_lds_dwordx4 v138, s[22:23]
	s_mov_b32 m0, s54
	s_nop 0
	global_load_lds_dwordx4 v134, s[22:23]
	s_waitcnt vmcnt(8)
	s_waitcnt lgkmcnt(0)
	s_setprio 1
	s_barrier
	v_mfma_f32_16x16x32_bf16 v[64:67], v[152:155], v[188:191], v[64:67]
	v_mfma_f32_16x16x32_bf16 v[60:63], v[160:163], v[188:191], v[60:63]
	v_mfma_f32_16x16x32_bf16 v[48:51], v[152:155], v[196:199], v[48:51]
	v_mfma_f32_16x16x32_bf16 v[44:47], v[160:163], v[196:199], v[44:47]
	v_mfma_f32_16x16x32_bf16 v[32:35], v[152:155], v[204:207], v[32:35]
	v_mfma_f32_16x16x32_bf16 v[28:31], v[160:163], v[204:207], v[28:31]
	v_mfma_f32_16x16x32_bf16 v[16:19], v[152:155], v[214:217], v[16:19]
	v_mfma_f32_16x16x32_bf16 v[12:15], v[160:163], v[214:217], v[12:15]
	v_mfma_f32_16x16x32_bf16 v[64:67], v[156:159], v[192:195], v[64:67]
	v_mfma_f32_16x16x32_bf16 v[60:63], v[168:171], v[192:195], v[60:63]
	v_mfma_f32_16x16x32_bf16 v[48:51], v[156:159], v[200:203], v[48:51]
	v_mfma_f32_16x16x32_bf16 v[44:47], v[168:171], v[200:203], v[44:47]
	v_mfma_f32_16x16x32_bf16 v[32:35], v[156:159], v[210:213], v[32:35]
	v_mfma_f32_16x16x32_bf16 v[28:31], v[168:171], v[210:213], v[28:31]
	v_mfma_f32_16x16x32_bf16 v[16:19], v[156:159], v[218:221], v[16:19]
	v_mfma_f32_16x16x32_bf16 v[12:15], v[168:171], v[218:221], v[12:15]
	v_mfma_f32_16x16x32_bf16 v[56:59], v[172:175], v[188:191], v[56:59]
	v_mfma_f32_16x16x32_bf16 v[52:55], v[180:183], v[188:191], v[52:55]
	v_mfma_f32_16x16x32_bf16 v[40:43], v[172:175], v[196:199], v[40:43]
	v_mfma_f32_16x16x32_bf16 v[36:39], v[180:183], v[196:199], v[36:39]
	v_mfma_f32_16x16x32_bf16 v[24:27], v[172:175], v[204:207], v[24:27]
	v_mfma_f32_16x16x32_bf16 v[20:23], v[180:183], v[204:207], v[20:23]
	v_mfma_f32_16x16x32_bf16 v[8:11], v[172:175], v[214:217], v[8:11]
	v_mfma_f32_16x16x32_bf16 v[4:7], v[180:183], v[214:217], v[4:7]
	v_mfma_f32_16x16x32_bf16 v[56:59], v[176:179], v[192:195], v[56:59]
	v_mfma_f32_16x16x32_bf16 v[52:55], v[184:187], v[192:195], v[52:55]
	v_mfma_f32_16x16x32_bf16 v[40:43], v[176:179], v[200:203], v[40:43]
	v_mfma_f32_16x16x32_bf16 v[36:39], v[184:187], v[200:203], v[36:39]
	v_mfma_f32_16x16x32_bf16 v[24:27], v[176:179], v[210:213], v[24:27]
	v_mfma_f32_16x16x32_bf16 v[20:23], v[184:187], v[210:213], v[20:23]
	v_mfma_f32_16x16x32_bf16 v[8:11], v[176:179], v[218:221], v[8:11]
	v_mfma_f32_16x16x32_bf16 v[4:7], v[184:187], v[218:221], v[4:7]
	s_barrier
	s_setprio 0
	s_add_u32 s2, s2, s98
	s_addc_u32 s3, s3, 0
	s_add_u32 s7, s7, 0x100
	s_addc_u32 s8, s8, 0
	s_add_i32 s99, s28, 2
	s_cmp_ge_u32 s99, s51
	s_mov_b32 s9, s28
	s_cbranch_scc0 .LBB0_832
	s_branch .Llast_832
.LBB0_832:
	s_add_i32 s28, s9, 2
	s_add_u32 s22, s2, s100
	s_addc_u32 s23, s3, 0
	s_add_i32 s29, 0, 0x10000
	s_cmp_eq_u32 s52, s9
	s_cselect_b32 s23, s1, s23
	s_cselect_b32 s22, s0, s22
	v_add_u32_e32 v2, s29, v147
	s_cselect_b32 s35, s21, s8
	s_cselect_b32 s34, s20, s7
	s_add_i32 s9, 0, 0x14000
	ds_read_b128 v[152:155], v2
	ds_read_b128 v[156:159], v2 offset:1024
	ds_read_b128 v[160:163], v2 offset:2048
	ds_read_b128 v[168:171], v2 offset:3072
	v_add_u32_e32 v2, s9, v147
	ds_read_b128 v[172:175], v2
	ds_read_b128 v[176:179], v2 offset:1024
	ds_read_b128 v[180:183], v2 offset:2048
	ds_read_b128 v[184:187], v2 offset:3072
	s_add_i32 m0, s47, 0xc000
	ds_read_b128 v[188:191], v150
	ds_read_b128 v[192:195], v150 offset:1024
	ds_read_b128 v[196:199], v150 offset:2048
	ds_read_b128 v[200:203], v150 offset:3072
	ds_read_b128 v[204:207], v150 offset:4096
	ds_read_b128 v[210:213], v150 offset:5120
	ds_read_b128 v[214:217], v150 offset:6144
	ds_read_b128 v[218:221], v150 offset:7168
	global_load_lds_dwordx4 v140, s[2:3]
	s_add_i32 m0, s47, 0xe000
	s_nop 0
	global_load_lds_dwordx4 v142, s[2:3]
	s_waitcnt vmcnt(8)
	s_waitcnt lgkmcnt(0)
	s_setprio 1
	s_barrier
	v_mfma_f32_16x16x32_bf16 v[128:131], v[152:155], v[188:191], v[128:131]
	v_mfma_f32_16x16x32_bf16 v[124:127], v[160:163], v[188:191], v[124:127]
	v_mfma_f32_16x16x32_bf16 v[112:115], v[152:155], v[196:199], v[112:115]
	v_mfma_f32_16x16x32_bf16 v[108:111], v[160:163], v[196:199], v[108:111]
	v_mfma_f32_16x16x32_bf16 v[96:99], v[152:155], v[204:207], v[96:99]
	v_mfma_f32_16x16x32_bf16 v[92:95], v[160:163], v[204:207], v[92:95]
	v_mfma_f32_16x16x32_bf16 v[80:83], v[152:155], v[214:217], v[80:83]
	v_mfma_f32_16x16x32_bf16 v[76:79], v[160:163], v[214:217], v[76:79]
	v_mfma_f32_16x16x32_bf16 v[128:131], v[156:159], v[192:195], v[128:131]
	v_mfma_f32_16x16x32_bf16 v[124:127], v[168:171], v[192:195], v[124:127]
	v_mfma_f32_16x16x32_bf16 v[112:115], v[156:159], v[200:203], v[112:115]
	v_mfma_f32_16x16x32_bf16 v[108:111], v[168:171], v[200:203], v[108:111]
	v_mfma_f32_16x16x32_bf16 v[96:99], v[156:159], v[210:213], v[96:99]
	v_mfma_f32_16x16x32_bf16 v[92:95], v[168:171], v[210:213], v[92:95]
	v_mfma_f32_16x16x32_bf16 v[80:83], v[156:159], v[218:221], v[80:83]
	v_mfma_f32_16x16x32_bf16 v[76:79], v[168:171], v[218:221], v[76:79]
	v_mfma_f32_16x16x32_bf16 v[120:123], v[172:175], v[188:191], v[120:123]
	v_mfma_f32_16x16x32_bf16 v[116:119], v[180:183], v[188:191], v[116:119]
	v_mfma_f32_16x16x32_bf16 v[104:107], v[172:175], v[196:199], v[104:107]
	v_mfma_f32_16x16x32_bf16 v[100:103], v[180:183], v[196:199], v[100:103]
	v_mfma_f32_16x16x32_bf16 v[88:91], v[172:175], v[204:207], v[88:91]
	v_mfma_f32_16x16x32_bf16 v[84:87], v[180:183], v[204:207], v[84:87]
	v_mfma_f32_16x16x32_bf16 v[72:75], v[172:175], v[214:217], v[72:75]
	v_mfma_f32_16x16x32_bf16 v[68:71], v[180:183], v[214:217], v[68:71]
	v_mfma_f32_16x16x32_bf16 v[120:123], v[176:179], v[192:195], v[120:123]
	v_mfma_f32_16x16x32_bf16 v[116:119], v[184:187], v[192:195], v[116:119]
	v_mfma_f32_16x16x32_bf16 v[104:107], v[176:179], v[200:203], v[104:107]
	v_mfma_f32_16x16x32_bf16 v[100:103], v[184:187], v[200:203], v[100:103]
	v_mfma_f32_16x16x32_bf16 v[88:91], v[176:179], v[210:213], v[88:91]
	v_mfma_f32_16x16x32_bf16 v[84:87], v[184:187], v[210:213], v[84:87]
	v_mfma_f32_16x16x32_bf16 v[72:75], v[176:179], v[218:221], v[72:75]
	v_mfma_f32_16x16x32_bf16 v[68:71], v[184:187], v[218:221], v[68:71]
	s_barrier
	s_setprio 0
	s_add_i32 s29, s29, s26
	s_mov_b32 m0, s29
	ds_read_b128 v[188:191], v150 offset:16384
	ds_read_b128 v[192:195], v150 offset:17408
	ds_read_b128 v[196:199], v150 offset:18432
	ds_read_b128 v[200:203], v150 offset:19456
	ds_read_b128 v[204:207], v150 offset:20480
	ds_read_b128 v[210:213], v150 offset:21504
	ds_read_b128 v[214:217], v150 offset:22528
	ds_read_b128 v[218:221], v150 offset:23552
	global_load_lds_dwordx4 v136, s[34:35]
	s_add_i32 m0, s29, 0x2000
	s_add_i32 s9, s9, s26
	global_load_lds_dwordx4 v132, s[34:35]
	s_add_u32 s34, s34, s16
	s_addc_u32 s35, s35, 0
	s_mov_b32 m0, s9
	s_nop 0
	global_load_lds_dwordx4 v136, s[34:35]
	s_add_i32 m0, s9, 0x2000
	s_nop 0
	global_load_lds_dwordx4 v132, s[34:35]
	s_mov_b32 m0, s47
	s_nop 0
	global_load_lds_dwordx4 v138, s[22:23]
	s_mov_b32 m0, s48
	s_nop 0
	global_load_lds_dwordx4 v134, s[22:23]
	s_waitcnt vmcnt(8)
	s_waitcnt lgkmcnt(0)
	s_setprio 1
	s_barrier
	v_mfma_f32_16x16x32_bf16 v[64:67], v[152:155], v[188:191], v[64:67]
	v_mfma_f32_16x16x32_bf16 v[60:63], v[160:163], v[188:191], v[60:63]
	v_mfma_f32_16x16x32_bf16 v[48:51], v[152:155], v[196:199], v[48:51]
	v_mfma_f32_16x16x32_bf16 v[44:47], v[160:163], v[196:199], v[44:47]
	v_mfma_f32_16x16x32_bf16 v[32:35], v[152:155], v[204:207], v[32:35]
	v_mfma_f32_16x16x32_bf16 v[28:31], v[160:163], v[204:207], v[28:31]
	v_mfma_f32_16x16x32_bf16 v[16:19], v[152:155], v[214:217], v[16:19]
	v_mfma_f32_16x16x32_bf16 v[12:15], v[160:163], v[214:217], v[12:15]
	v_mfma_f32_16x16x32_bf16 v[64:67], v[156:159], v[192:195], v[64:67]
	v_mfma_f32_16x16x32_bf16 v[60:63], v[168:171], v[192:195], v[60:63]
	v_mfma_f32_16x16x32_bf16 v[48:51], v[156:159], v[200:203], v[48:51]
	v_mfma_f32_16x16x32_bf16 v[44:47], v[168:171], v[200:203], v[44:47]
	v_mfma_f32_16x16x32_bf16 v[32:35], v[156:159], v[210:213], v[32:35]
	v_mfma_f32_16x16x32_bf16 v[28:31], v[168:171], v[210:213], v[28:31]
	v_mfma_f32_16x16x32_bf16 v[16:19], v[156:159], v[218:221], v[16:19]
	v_mfma_f32_16x16x32_bf16 v[12:15], v[168:171], v[218:221], v[12:15]
	v_mfma_f32_16x16x32_bf16 v[56:59], v[172:175], v[188:191], v[56:59]
	v_mfma_f32_16x16x32_bf16 v[52:55], v[180:183], v[188:191], v[52:55]
	v_mfma_f32_16x16x32_bf16 v[40:43], v[172:175], v[196:199], v[40:43]
	v_mfma_f32_16x16x32_bf16 v[36:39], v[180:183], v[196:199], v[36:39]
	v_mfma_f32_16x16x32_bf16 v[24:27], v[172:175], v[204:207], v[24:27]
	v_mfma_f32_16x16x32_bf16 v[20:23], v[180:183], v[204:207], v[20:23]
	v_mfma_f32_16x16x32_bf16 v[8:11], v[172:175], v[214:217], v[8:11]
	v_mfma_f32_16x16x32_bf16 v[4:7], v[180:183], v[214:217], v[4:7]
	v_mfma_f32_16x16x32_bf16 v[56:59], v[176:179], v[192:195], v[56:59]
	v_mfma_f32_16x16x32_bf16 v[52:55], v[184:187], v[192:195], v[52:55]
	v_mfma_f32_16x16x32_bf16 v[40:43], v[176:179], v[200:203], v[40:43]
	v_mfma_f32_16x16x32_bf16 v[36:39], v[184:187], v[200:203], v[36:39]
	v_mfma_f32_16x16x32_bf16 v[24:27], v[176:179], v[210:213], v[24:27]
	v_mfma_f32_16x16x32_bf16 v[20:23], v[184:187], v[210:213], v[20:23]
	v_mfma_f32_16x16x32_bf16 v[8:11], v[176:179], v[218:221], v[8:11]
	v_mfma_f32_16x16x32_bf16 v[4:7], v[184:187], v[218:221], v[4:7]
	s_barrier
	s_setprio 0
	s_add_i32 s9, 0, 0x18000
	v_add_u32_e32 v2, s9, v147
	s_add_i32 s29, 0, 0x1c000
	ds_read_b128 v[152:155], v2
	ds_read_b128 v[156:159], v2 offset:1024
	ds_read_b128 v[160:163], v2 offset:2048
	ds_read_b128 v[168:171], v2 offset:3072
	v_add_u32_e32 v2, s29, v147
	ds_read_b128 v[172:175], v2
	ds_read_b128 v[176:179], v2 offset:1024
	ds_read_b128 v[180:183], v2 offset:2048
	ds_read_b128 v[184:187], v2 offset:3072
	s_add_u32 s22, s22, s16
	s_addc_u32 s23, s23, 0
	s_mov_b32 m0, s49
	ds_read_b128 v[188:191], v150 offset:32768
	ds_read_b128 v[192:195], v150 offset:33792
	ds_read_b128 v[196:199], v150 offset:34816
	ds_read_b128 v[200:203], v150 offset:35840
	ds_read_b128 v[204:207], v150 offset:36864
	ds_read_b128 v[210:213], v150 offset:37888
	ds_read_b128 v[214:217], v150 offset:38912
	ds_read_b128 v[218:221], v150 offset:39936
	global_load_lds_dwordx4 v138, s[22:23]
	s_mov_b32 m0, s50
	s_nop 0
	global_load_lds_dwordx4 v134, s[22:23]
	s_waitcnt vmcnt(8)
	s_waitcnt lgkmcnt(0)
	s_setprio 1
	s_barrier
	v_mfma_f32_16x16x32_bf16 v[128:131], v[152:155], v[188:191], v[128:131]
	v_mfma_f32_16x16x32_bf16 v[124:127], v[160:163], v[188:191], v[124:127]
	v_mfma_f32_16x16x32_bf16 v[112:115], v[152:155], v[196:199], v[112:115]
	v_mfma_f32_16x16x32_bf16 v[108:111], v[160:163], v[196:199], v[108:111]
	v_mfma_f32_16x16x32_bf16 v[96:99], v[152:155], v[204:207], v[96:99]
	v_mfma_f32_16x16x32_bf16 v[92:95], v[160:163], v[204:207], v[92:95]
	v_mfma_f32_16x16x32_bf16 v[80:83], v[152:155], v[214:217], v[80:83]
	v_mfma_f32_16x16x32_bf16 v[76:79], v[160:163], v[214:217], v[76:79]
	v_mfma_f32_16x16x32_bf16 v[128:131], v[156:159], v[192:195], v[128:131]
	v_mfma_f32_16x16x32_bf16 v[124:127], v[168:171], v[192:195], v[124:127]
	v_mfma_f32_16x16x32_bf16 v[112:115], v[156:159], v[200:203], v[112:115]
	v_mfma_f32_16x16x32_bf16 v[108:111], v[168:171], v[200:203], v[108:111]
	v_mfma_f32_16x16x32_bf16 v[96:99], v[156:159], v[210:213], v[96:99]
	v_mfma_f32_16x16x32_bf16 v[92:95], v[168:171], v[210:213], v[92:95]
	v_mfma_f32_16x16x32_bf16 v[80:83], v[156:159], v[218:221], v[80:83]
	v_mfma_f32_16x16x32_bf16 v[76:79], v[168:171], v[218:221], v[76:79]
	v_mfma_f32_16x16x32_bf16 v[120:123], v[172:175], v[188:191], v[120:123]
	v_mfma_f32_16x16x32_bf16 v[116:119], v[180:183], v[188:191], v[116:119]
	v_mfma_f32_16x16x32_bf16 v[104:107], v[172:175], v[196:199], v[104:107]
	v_mfma_f32_16x16x32_bf16 v[100:103], v[180:183], v[196:199], v[100:103]
	v_mfma_f32_16x16x32_bf16 v[88:91], v[172:175], v[204:207], v[88:91]
	v_mfma_f32_16x16x32_bf16 v[84:87], v[180:183], v[204:207], v[84:87]
	v_mfma_f32_16x16x32_bf16 v[72:75], v[172:175], v[214:217], v[72:75]
	v_mfma_f32_16x16x32_bf16 v[68:71], v[180:183], v[214:217], v[68:71]
	v_mfma_f32_16x16x32_bf16 v[120:123], v[176:179], v[192:195], v[120:123]
	v_mfma_f32_16x16x32_bf16 v[116:119], v[184:187], v[192:195], v[116:119]
	v_mfma_f32_16x16x32_bf16 v[104:107], v[176:179], v[200:203], v[104:107]
	v_mfma_f32_16x16x32_bf16 v[100:103], v[184:187], v[200:203], v[100:103]
	v_mfma_f32_16x16x32_bf16 v[88:91], v[176:179], v[210:213], v[88:91]
	v_mfma_f32_16x16x32_bf16 v[84:87], v[184:187], v[210:213], v[84:87]
	v_mfma_f32_16x16x32_bf16 v[72:75], v[176:179], v[218:221], v[72:75]
	v_mfma_f32_16x16x32_bf16 v[68:71], v[184:187], v[218:221], v[68:71]
	s_barrier
	s_setprio 0
	s_add_i32 s9, s9, s26
	s_mov_b32 m0, s9
	ds_read_b128 v[188:191], v150 offset:49152
	ds_read_b128 v[192:195], v150 offset:50176
	ds_read_b128 v[196:199], v150 offset:51200
	ds_read_b128 v[200:203], v150 offset:52224
	ds_read_b128 v[204:207], v150 offset:53248
	ds_read_b128 v[210:213], v150 offset:54272
	ds_read_b128 v[214:217], v150 offset:55296
	ds_read_b128 v[218:221], v150 offset:56320
	s_sub_u32 s34, s34, s16
	s_subb_u32 s35, s35, 0
	s_add_u32 s34, s34, 0x80
	s_addc_u32 s35, s35, 0
	global_load_lds_dwordx4 v136, s[34:35]
	s_add_i32 m0, s9, 0x2000
	s_add_i32 s9, s29, s26
	global_load_lds_dwordx4 v132, s[34:35]
	s_mov_b32 m0, s9
	s_nop 0
	s_add_u32 s34, s34, s16
	s_addc_u32 s35, s35, 0
	global_load_lds_dwordx4 v136, s[34:35]
	s_add_i32 m0, s9, 0x2000
	s_nop 0
	global_load_lds_dwordx4 v132, s[34:35]
	s_mov_b32 m0, s53
	s_nop 0
	s_sub_u32 s22, s22, s16
	s_subb_u32 s23, s23, 0
	s_add_u32 s22, s22, s100
	s_addc_u32 s23, s23, 0
	global_load_lds_dwordx4 v138, s[22:23]
	s_mov_b32 m0, s54
	s_nop 0
	global_load_lds_dwordx4 v134, s[22:23]
	s_waitcnt vmcnt(8)
	s_waitcnt lgkmcnt(0)
	s_setprio 1
	s_barrier
	v_mfma_f32_16x16x32_bf16 v[64:67], v[152:155], v[188:191], v[64:67]
	v_mfma_f32_16x16x32_bf16 v[60:63], v[160:163], v[188:191], v[60:63]
	v_mfma_f32_16x16x32_bf16 v[48:51], v[152:155], v[196:199], v[48:51]
	v_mfma_f32_16x16x32_bf16 v[44:47], v[160:163], v[196:199], v[44:47]
	v_mfma_f32_16x16x32_bf16 v[32:35], v[152:155], v[204:207], v[32:35]
	v_mfma_f32_16x16x32_bf16 v[28:31], v[160:163], v[204:207], v[28:31]
	v_mfma_f32_16x16x32_bf16 v[16:19], v[152:155], v[214:217], v[16:19]
	v_mfma_f32_16x16x32_bf16 v[12:15], v[160:163], v[214:217], v[12:15]
	v_mfma_f32_16x16x32_bf16 v[64:67], v[156:159], v[192:195], v[64:67]
	v_mfma_f32_16x16x32_bf16 v[60:63], v[168:171], v[192:195], v[60:63]
	v_mfma_f32_16x16x32_bf16 v[48:51], v[156:159], v[200:203], v[48:51]
	v_mfma_f32_16x16x32_bf16 v[44:47], v[168:171], v[200:203], v[44:47]
	v_mfma_f32_16x16x32_bf16 v[32:35], v[156:159], v[210:213], v[32:35]
	v_mfma_f32_16x16x32_bf16 v[28:31], v[168:171], v[210:213], v[28:31]
	v_mfma_f32_16x16x32_bf16 v[16:19], v[156:159], v[218:221], v[16:19]
	v_mfma_f32_16x16x32_bf16 v[12:15], v[168:171], v[218:221], v[12:15]
	v_mfma_f32_16x16x32_bf16 v[56:59], v[172:175], v[188:191], v[56:59]
	v_mfma_f32_16x16x32_bf16 v[52:55], v[180:183], v[188:191], v[52:55]
	v_mfma_f32_16x16x32_bf16 v[40:43], v[172:175], v[196:199], v[40:43]
	v_mfma_f32_16x16x32_bf16 v[36:39], v[180:183], v[196:199], v[36:39]
	v_mfma_f32_16x16x32_bf16 v[24:27], v[172:175], v[204:207], v[24:27]
	v_mfma_f32_16x16x32_bf16 v[20:23], v[180:183], v[204:207], v[20:23]
	v_mfma_f32_16x16x32_bf16 v[8:11], v[172:175], v[214:217], v[8:11]
	v_mfma_f32_16x16x32_bf16 v[4:7], v[180:183], v[214:217], v[4:7]
	v_mfma_f32_16x16x32_bf16 v[56:59], v[176:179], v[192:195], v[56:59]
	v_mfma_f32_16x16x32_bf16 v[52:55], v[184:187], v[192:195], v[52:55]
	v_mfma_f32_16x16x32_bf16 v[40:43], v[176:179], v[200:203], v[40:43]
	v_mfma_f32_16x16x32_bf16 v[36:39], v[184:187], v[200:203], v[36:39]
	v_mfma_f32_16x16x32_bf16 v[24:27], v[176:179], v[210:213], v[24:27]
	v_mfma_f32_16x16x32_bf16 v[20:23], v[184:187], v[210:213], v[20:23]
	v_mfma_f32_16x16x32_bf16 v[8:11], v[176:179], v[218:221], v[8:11]
	v_mfma_f32_16x16x32_bf16 v[4:7], v[184:187], v[218:221], v[4:7]
	s_barrier
	s_setprio 0
	s_add_u32 s2, s2, s98
	s_addc_u32 s3, s3, 0
	s_add_u32 s7, s7, 0x100
	s_addc_u32 s8, s8, 0
	s_add_i32 s99, s28, 2
	s_cmp_ge_u32 s99, s51
	s_mov_b32 s9, s28
	s_cbranch_scc0 .LBB0_832
.Llast_832:
	s_add_i32 s28, s9, 2
	s_add_u32 s22, s2, s100
	s_addc_u32 s23, s3, 0
	s_add_i32 s29, 0, 0x10000
	s_cmp_eq_u32 s52, s9
	s_cselect_b32 s23, s1, s23
	s_cselect_b32 s22, s0, s22
	v_add_u32_e32 v2, s29, v147
	s_cselect_b32 s35, s21, s8
	s_cselect_b32 s34, s20, s7
	s_add_i32 s9, 0, 0x14000
	ds_read_b128 v[152:155], v2
	ds_read_b128 v[156:159], v2 offset:1024
	ds_read_b128 v[160:163], v2 offset:2048
	ds_read_b128 v[168:171], v2 offset:3072
	v_add_u32_e32 v2, s9, v147
	ds_read_b128 v[172:175], v2
	ds_read_b128 v[176:179], v2 offset:1024
	ds_read_b128 v[180:183], v2 offset:2048
	ds_read_b128 v[184:187], v2 offset:3072
	s_add_i32 m0, s47, 0xc000
	ds_read_b128 v[188:191], v150
	ds_read_b128 v[192:195], v150 offset:1024
	ds_read_b128 v[196:199], v150 offset:2048
	ds_read_b128 v[200:203], v150 offset:3072
	ds_read_b128 v[204:207], v150 offset:4096
	ds_read_b128 v[210:213], v150 offset:5120
	ds_read_b128 v[214:217], v150 offset:6144
	ds_read_b128 v[218:221], v150 offset:7168
	global_load_lds_dwordx4 v140, s[2:3]
	s_add_i32 m0, s47, 0xe000
	s_nop 0
	global_load_lds_dwordx4 v142, s[2:3]
	s_waitcnt vmcnt(8)
	s_waitcnt lgkmcnt(0)
	s_setprio 1
	s_barrier
	v_mfma_f32_16x16x32_bf16 v[128:131], v[152:155], v[188:191], v[128:131]
	v_mfma_f32_16x16x32_bf16 v[124:127], v[160:163], v[188:191], v[124:127]
	v_mfma_f32_16x16x32_bf16 v[112:115], v[152:155], v[196:199], v[112:115]
	v_mfma_f32_16x16x32_bf16 v[108:111], v[160:163], v[196:199], v[108:111]
	v_mfma_f32_16x16x32_bf16 v[96:99], v[152:155], v[204:207], v[96:99]
	v_mfma_f32_16x16x32_bf16 v[92:95], v[160:163], v[204:207], v[92:95]
	v_mfma_f32_16x16x32_bf16 v[80:83], v[152:155], v[214:217], v[80:83]
	v_mfma_f32_16x16x32_bf16 v[76:79], v[160:163], v[214:217], v[76:79]
	v_mfma_f32_16x16x32_bf16 v[128:131], v[156:159], v[192:195], v[128:131]
	v_mfma_f32_16x16x32_bf16 v[124:127], v[168:171], v[192:195], v[124:127]
	v_mfma_f32_16x16x32_bf16 v[112:115], v[156:159], v[200:203], v[112:115]
	v_mfma_f32_16x16x32_bf16 v[108:111], v[168:171], v[200:203], v[108:111]
	v_mfma_f32_16x16x32_bf16 v[96:99], v[156:159], v[210:213], v[96:99]
	v_mfma_f32_16x16x32_bf16 v[92:95], v[168:171], v[210:213], v[92:95]
	v_mfma_f32_16x16x32_bf16 v[80:83], v[156:159], v[218:221], v[80:83]
	v_mfma_f32_16x16x32_bf16 v[76:79], v[168:171], v[218:221], v[76:79]
	v_mfma_f32_16x16x32_bf16 v[120:123], v[172:175], v[188:191], v[120:123]
	v_mfma_f32_16x16x32_bf16 v[116:119], v[180:183], v[188:191], v[116:119]
	v_mfma_f32_16x16x32_bf16 v[104:107], v[172:175], v[196:199], v[104:107]
	v_mfma_f32_16x16x32_bf16 v[100:103], v[180:183], v[196:199], v[100:103]
	v_mfma_f32_16x16x32_bf16 v[88:91], v[172:175], v[204:207], v[88:91]
	v_mfma_f32_16x16x32_bf16 v[84:87], v[180:183], v[204:207], v[84:87]
	v_mfma_f32_16x16x32_bf16 v[72:75], v[172:175], v[214:217], v[72:75]
	v_mfma_f32_16x16x32_bf16 v[68:71], v[180:183], v[214:217], v[68:71]
	v_mfma_f32_16x16x32_bf16 v[120:123], v[176:179], v[192:195], v[120:123]
	v_mfma_f32_16x16x32_bf16 v[116:119], v[184:187], v[192:195], v[116:119]
	v_mfma_f32_16x16x32_bf16 v[104:107], v[176:179], v[200:203], v[104:107]
	v_mfma_f32_16x16x32_bf16 v[100:103], v[184:187], v[200:203], v[100:103]
	v_mfma_f32_16x16x32_bf16 v[88:91], v[176:179], v[210:213], v[88:91]
	v_mfma_f32_16x16x32_bf16 v[84:87], v[184:187], v[210:213], v[84:87]
	v_mfma_f32_16x16x32_bf16 v[72:75], v[176:179], v[218:221], v[72:75]
	v_mfma_f32_16x16x32_bf16 v[68:71], v[184:187], v[218:221], v[68:71]
	s_barrier
	s_setprio 0
	s_add_i32 s29, s29, s26
	s_mov_b32 m0, s29
	ds_read_b128 v[188:191], v150 offset:16384
	ds_read_b128 v[192:195], v150 offset:17408
	ds_read_b128 v[196:199], v150 offset:18432
	ds_read_b128 v[200:203], v150 offset:19456
	ds_read_b128 v[204:207], v150 offset:20480
	ds_read_b128 v[210:213], v150 offset:21504
	ds_read_b128 v[214:217], v150 offset:22528
	ds_read_b128 v[218:221], v150 offset:23552
	global_load_lds_dwordx4 v136, s[34:35]
	s_add_i32 m0, s29, 0x2000
	s_add_i32 s9, s9, s26
	global_load_lds_dwordx4 v132, s[34:35]
	s_add_u32 s34, s34, s16
	s_addc_u32 s35, s35, 0
	s_mov_b32 m0, s9
	s_nop 0
	global_load_lds_dwordx4 v136, s[34:35]
	s_add_i32 m0, s9, 0x2000
	s_nop 0
	global_load_lds_dwordx4 v132, s[34:35]
	s_mov_b32 m0, s47
	s_nop 0
	global_load_lds_dwordx4 v138, s[22:23]
	s_mov_b32 m0, s48
	s_nop 0
	global_load_lds_dwordx4 v134, s[22:23]
	s_waitcnt vmcnt(8)
	s_waitcnt lgkmcnt(0)
	s_setprio 1
	s_barrier
	v_mfma_f32_16x16x32_bf16 v[64:67], v[152:155], v[188:191], v[64:67]
	v_mfma_f32_16x16x32_bf16 v[60:63], v[160:163], v[188:191], v[60:63]
	v_mfma_f32_16x16x32_bf16 v[48:51], v[152:155], v[196:199], v[48:51]
	v_mfma_f32_16x16x32_bf16 v[44:47], v[160:163], v[196:199], v[44:47]
	v_mfma_f32_16x16x32_bf16 v[32:35], v[152:155], v[204:207], v[32:35]
	v_mfma_f32_16x16x32_bf16 v[28:31], v[160:163], v[204:207], v[28:31]
	v_mfma_f32_16x16x32_bf16 v[16:19], v[152:155], v[214:217], v[16:19]
	v_mfma_f32_16x16x32_bf16 v[12:15], v[160:163], v[214:217], v[12:15]
	v_mfma_f32_16x16x32_bf16 v[64:67], v[156:159], v[192:195], v[64:67]
	v_mfma_f32_16x16x32_bf16 v[60:63], v[168:171], v[192:195], v[60:63]
	v_mfma_f32_16x16x32_bf16 v[48:51], v[156:159], v[200:203], v[48:51]
	v_mfma_f32_16x16x32_bf16 v[44:47], v[168:171], v[200:203], v[44:47]
	v_mfma_f32_16x16x32_bf16 v[32:35], v[156:159], v[210:213], v[32:35]
	v_mfma_f32_16x16x32_bf16 v[28:31], v[168:171], v[210:213], v[28:31]
	v_mfma_f32_16x16x32_bf16 v[16:19], v[156:159], v[218:221], v[16:19]
	v_mfma_f32_16x16x32_bf16 v[12:15], v[168:171], v[218:221], v[12:15]
	v_mfma_f32_16x16x32_bf16 v[56:59], v[172:175], v[188:191], v[56:59]
	v_mfma_f32_16x16x32_bf16 v[52:55], v[180:183], v[188:191], v[52:55]
	v_mfma_f32_16x16x32_bf16 v[40:43], v[172:175], v[196:199], v[40:43]
	v_mfma_f32_16x16x32_bf16 v[36:39], v[180:183], v[196:199], v[36:39]
	v_mfma_f32_16x16x32_bf16 v[24:27], v[172:175], v[204:207], v[24:27]
	v_mfma_f32_16x16x32_bf16 v[20:23], v[180:183], v[204:207], v[20:23]
	v_mfma_f32_16x16x32_bf16 v[8:11], v[172:175], v[214:217], v[8:11]
	v_mfma_f32_16x16x32_bf16 v[4:7], v[180:183], v[214:217], v[4:7]
	v_mfma_f32_16x16x32_bf16 v[56:59], v[176:179], v[192:195], v[56:59]
	v_mfma_f32_16x16x32_bf16 v[52:55], v[184:187], v[192:195], v[52:55]
	v_mfma_f32_16x16x32_bf16 v[40:43], v[176:179], v[200:203], v[40:43]
	v_mfma_f32_16x16x32_bf16 v[36:39], v[184:187], v[200:203], v[36:39]
	v_mfma_f32_16x16x32_bf16 v[24:27], v[176:179], v[210:213], v[24:27]
	v_mfma_f32_16x16x32_bf16 v[20:23], v[184:187], v[210:213], v[20:23]
	v_mfma_f32_16x16x32_bf16 v[8:11], v[176:179], v[218:221], v[8:11]
	v_mfma_f32_16x16x32_bf16 v[4:7], v[184:187], v[218:221], v[4:7]
	s_barrier
	s_setprio 0
	s_add_i32 s9, 0, 0x18000
	v_add_u32_e32 v2, s9, v147
	s_add_i32 s29, 0, 0x1c000
	ds_read_b128 v[152:155], v2
	ds_read_b128 v[156:159], v2 offset:1024
	ds_read_b128 v[160:163], v2 offset:2048
	ds_read_b128 v[168:171], v2 offset:3072
	v_add_u32_e32 v2, s29, v147
	ds_read_b128 v[172:175], v2
	ds_read_b128 v[176:179], v2 offset:1024
	ds_read_b128 v[180:183], v2 offset:2048
	ds_read_b128 v[184:187], v2 offset:3072
	s_add_u32 s22, s22, s16
	s_addc_u32 s23, s23, 0
	s_mov_b32 m0, s49
	ds_read_b128 v[188:191], v150 offset:32768
	ds_read_b128 v[192:195], v150 offset:33792
	ds_read_b128 v[196:199], v150 offset:34816
	ds_read_b128 v[200:203], v150 offset:35840
	ds_read_b128 v[204:207], v150 offset:36864
	ds_read_b128 v[210:213], v150 offset:37888
	ds_read_b128 v[214:217], v150 offset:38912
	ds_read_b128 v[218:221], v150 offset:39936
	global_load_lds_dwordx4 v138, s[22:23]
	s_mov_b32 m0, s50
	s_nop 0
	global_load_lds_dwordx4 v134, s[22:23]
	s_waitcnt vmcnt(8)
	s_waitcnt lgkmcnt(0)
	s_setprio 1
	s_barrier
	v_mfma_f32_16x16x32_bf16 v[128:131], v[152:155], v[188:191], v[128:131]
	v_mfma_f32_16x16x32_bf16 v[124:127], v[160:163], v[188:191], v[124:127]
	v_mfma_f32_16x16x32_bf16 v[112:115], v[152:155], v[196:199], v[112:115]
	v_mfma_f32_16x16x32_bf16 v[108:111], v[160:163], v[196:199], v[108:111]
	v_mfma_f32_16x16x32_bf16 v[96:99], v[152:155], v[204:207], v[96:99]
	v_mfma_f32_16x16x32_bf16 v[92:95], v[160:163], v[204:207], v[92:95]
	v_mfma_f32_16x16x32_bf16 v[80:83], v[152:155], v[214:217], v[80:83]
	v_mfma_f32_16x16x32_bf16 v[76:79], v[160:163], v[214:217], v[76:79]
	v_mfma_f32_16x16x32_bf16 v[128:131], v[156:159], v[192:195], v[128:131]
	v_mfma_f32_16x16x32_bf16 v[124:127], v[168:171], v[192:195], v[124:127]
	v_mfma_f32_16x16x32_bf16 v[112:115], v[156:159], v[200:203], v[112:115]
	v_mfma_f32_16x16x32_bf16 v[108:111], v[168:171], v[200:203], v[108:111]
	v_mfma_f32_16x16x32_bf16 v[96:99], v[156:159], v[210:213], v[96:99]
	v_mfma_f32_16x16x32_bf16 v[92:95], v[168:171], v[210:213], v[92:95]
	v_mfma_f32_16x16x32_bf16 v[80:83], v[156:159], v[218:221], v[80:83]
	v_mfma_f32_16x16x32_bf16 v[76:79], v[168:171], v[218:221], v[76:79]
	v_mfma_f32_16x16x32_bf16 v[120:123], v[172:175], v[188:191], v[120:123]
	v_mfma_f32_16x16x32_bf16 v[116:119], v[180:183], v[188:191], v[116:119]
	v_mfma_f32_16x16x32_bf16 v[104:107], v[172:175], v[196:199], v[104:107]
	v_mfma_f32_16x16x32_bf16 v[100:103], v[180:183], v[196:199], v[100:103]
	v_mfma_f32_16x16x32_bf16 v[88:91], v[172:175], v[204:207], v[88:91]
	v_mfma_f32_16x16x32_bf16 v[84:87], v[180:183], v[204:207], v[84:87]
	v_mfma_f32_16x16x32_bf16 v[72:75], v[172:175], v[214:217], v[72:75]
	v_mfma_f32_16x16x32_bf16 v[68:71], v[180:183], v[214:217], v[68:71]
	v_mfma_f32_16x16x32_bf16 v[120:123], v[176:179], v[192:195], v[120:123]
	v_mfma_f32_16x16x32_bf16 v[116:119], v[184:187], v[192:195], v[116:119]
	v_mfma_f32_16x16x32_bf16 v[104:107], v[176:179], v[200:203], v[104:107]
	v_mfma_f32_16x16x32_bf16 v[100:103], v[184:187], v[200:203], v[100:103]
	v_mfma_f32_16x16x32_bf16 v[88:91], v[176:179], v[210:213], v[88:91]
	v_mfma_f32_16x16x32_bf16 v[84:87], v[184:187], v[210:213], v[84:87]
	v_mfma_f32_16x16x32_bf16 v[72:75], v[176:179], v[218:221], v[72:75]
	v_mfma_f32_16x16x32_bf16 v[68:71], v[184:187], v[218:221], v[68:71]
	s_barrier
	s_setprio 0
	s_add_i32 s9, s9, s26
	s_mov_b32 m0, s9
	ds_read_b128 v[188:191], v150 offset:49152
	ds_read_b128 v[192:195], v150 offset:50176
	ds_read_b128 v[196:199], v150 offset:51200
	ds_read_b128 v[200:203], v150 offset:52224
	ds_read_b128 v[204:207], v150 offset:53248
	ds_read_b128 v[210:213], v150 offset:54272
	ds_read_b128 v[214:217], v150 offset:55296
	ds_read_b128 v[218:221], v150 offset:56320
	s_sub_u32 s34, s34, s16
	s_subb_u32 s35, s35, 0
	s_add_u32 s34, s34, 0x80
	s_addc_u32 s35, s35, 0
	global_load_lds_dwordx4 v136, s[34:35]
	s_add_i32 m0, s9, 0x2000
	s_add_i32 s9, s29, s26
	global_load_lds_dwordx4 v132, s[34:35]
	s_mov_b32 m0, s9
	s_nop 0
	s_add_u32 s34, s34, s16
	s_addc_u32 s35, s35, 0
	global_load_lds_dwordx4 v136, s[34:35]
	s_add_i32 m0, s9, 0x2000
	s_nop 0
	global_load_lds_dwordx4 v132, s[34:35]
	s_mov_b32 m0, s53
	s_nop 0
	s_sub_u32 s22, s22, s16
	s_subb_u32 s23, s23, 0
	s_add_u32 s22, s22, s100
	s_addc_u32 s23, s23, 0
	global_load_lds_dwordx4 v138, s[22:23]
	s_mov_b32 m0, s54
	s_nop 0
	global_load_lds_dwordx4 v134, s[22:23]
	s_waitcnt vmcnt(8)
	s_waitcnt lgkmcnt(0)
	s_setprio 1
	s_barrier
	v_mfma_f32_16x16x32_bf16 v[64:67], v[152:155], v[188:191], v[64:67]
	v_mfma_f32_16x16x32_bf16 v[60:63], v[160:163], v[188:191], v[60:63]
	v_mfma_f32_16x16x32_bf16 v[48:51], v[152:155], v[196:199], v[48:51]
	v_mfma_f32_16x16x32_bf16 v[44:47], v[160:163], v[196:199], v[44:47]
	v_mfma_f32_16x16x32_bf16 v[32:35], v[152:155], v[204:207], v[32:35]
	v_mfma_f32_16x16x32_bf16 v[28:31], v[160:163], v[204:207], v[28:31]
	v_mfma_f32_16x16x32_bf16 v[16:19], v[152:155], v[214:217], v[16:19]
	v_mfma_f32_16x16x32_bf16 v[12:15], v[160:163], v[214:217], v[12:15]
	v_mfma_f32_16x16x32_bf16 v[64:67], v[156:159], v[192:195], v[64:67]
	v_mfma_f32_16x16x32_bf16 v[60:63], v[168:171], v[192:195], v[60:63]
	v_mfma_f32_16x16x32_bf16 v[48:51], v[156:159], v[200:203], v[48:51]
	v_mfma_f32_16x16x32_bf16 v[44:47], v[168:171], v[200:203], v[44:47]
	v_mfma_f32_16x16x32_bf16 v[32:35], v[156:159], v[210:213], v[32:35]
	v_mfma_f32_16x16x32_bf16 v[28:31], v[168:171], v[210:213], v[28:31]
	v_mfma_f32_16x16x32_bf16 v[16:19], v[156:159], v[218:221], v[16:19]
	v_mfma_f32_16x16x32_bf16 v[12:15], v[168:171], v[218:221], v[12:15]
	v_mfma_f32_16x16x32_bf16 v[56:59], v[172:175], v[188:191], v[56:59]
	v_mfma_f32_16x16x32_bf16 v[52:55], v[180:183], v[188:191], v[52:55]
	v_mfma_f32_16x16x32_bf16 v[40:43], v[172:175], v[196:199], v[40:43]
	v_mfma_f32_16x16x32_bf16 v[36:39], v[180:183], v[196:199], v[36:39]
	v_mfma_f32_16x16x32_bf16 v[24:27], v[172:175], v[204:207], v[24:27]
	v_mfma_f32_16x16x32_bf16 v[20:23], v[180:183], v[204:207], v[20:23]
	v_mfma_f32_16x16x32_bf16 v[8:11], v[172:175], v[214:217], v[8:11]
	v_mfma_f32_16x16x32_bf16 v[4:7], v[180:183], v[214:217], v[4:7]
	v_mfma_f32_16x16x32_bf16 v[56:59], v[176:179], v[192:195], v[56:59]
	v_mfma_f32_16x16x32_bf16 v[52:55], v[184:187], v[192:195], v[52:55]
	v_mfma_f32_16x16x32_bf16 v[40:43], v[176:179], v[200:203], v[40:43]
	v_mfma_f32_16x16x32_bf16 v[36:39], v[184:187], v[200:203], v[36:39]
	v_mfma_f32_16x16x32_bf16 v[24:27], v[176:179], v[210:213], v[24:27]
	v_mfma_f32_16x16x32_bf16 v[20:23], v[184:187], v[210:213], v[20:23]
	v_mfma_f32_16x16x32_bf16 v[8:11], v[176:179], v[218:221], v[8:11]
	v_mfma_f32_16x16x32_bf16 v[4:7], v[184:187], v[218:221], v[4:7]
	s_setprio 0
	s_add_u32 s2, s2, s98
	s_addc_u32 s3, s3, 0
	s_add_u32 s7, s7, 0x100
	s_addc_u32 s8, s8, 0
	s_mov_b32 s9, s28
